# MFMA order in all four K-loops: the two k-steps of each accumulator issued back-to-back (SrcC forwarding chain), on top of DMA re-layout + 4/4/4/4 balancing
# speedup vs baseline: 1.0228x; 1.0106x over previous
; #define PG8_STAGE(bufoff, gbase, voff) do { _Pragma("unroll") for (int _i = 0; _i < 2; ++_i) \
;         __builtin_amdgcn_global_load_lds((const unsigned*)((const char*)(gbase) + (voff)[_i]), (LAS unsigned*)(lds + (bufoff) + ldsw + _i * 8192), 16, 0, 0); } while (0)
; #define PG8_LDA(dst, b, h) do { _Pragma("unroll") for (int m = 0; m < 4; ++m) _Pragma("unroll") for (int k = 0; k < 2; ++k) dst[m][k] = *(const LAS bf16x8*)(lds + PG8_SA(b, h) + aoff + m * 2048 + k * 1024); } while (0)
; #define PG8_LDB(dst, b, h) do { _Pragma("unroll") for (int n = 0; n < 2; ++n) _Pragma("unroll") for (int k = 0; k < 2; ++k) dst[n][k] = *(const LAS bf16x8*)(lds + PG8_SB(b, h) + boff + n * 2048 + k * 1024); } while (0)
; #define PG8_MMA(ai, bj, At, Bt) do { __builtin_amdgcn_s_setprio(3); _Pragma("unroll") for (int m = 0; m < 4; ++m) _Pragma("unroll") for (int n = 0; n < 2; ++n) _Pragma("unroll") for (int k = 0; k < 2; ++k) \
;         acc[ai][bj][m][n] = __builtin_amdgcn_mfma_f32_16x16x32_bf16(Bt[n][k], At[m][k], acc[ai][bj][m][n], 0, 0, 0); __builtin_amdgcn_s_setprio(0); } while (0)
; #define PG8_WAIT_V(n) asm volatile("s_waitcnt vmcnt(" #n ")" ::: "memory")
; #define PG8_WAIT_L(n) asm volatile("s_waitcnt lgkmcnt(" #n ")" ::: "memory")
; #define PG8_BAR __builtin_amdgcn_s_barrier()
; #define PG8_SCHED __builtin_amdgcn_sched_barrier(0)
; template <class Epi, class Sched, bool ALIGN_EPI = false, bool SP2 = false>
; __device__ __forceinline__ void gemm_phase(LAS unsigned char* lds, const Gemm g, const Sched& S, const Epi& E) {
;     ...
;             PG8_LDB(B0, 0, 0); PG8_LDB(B1, 0, 1); PG8_SCHED; PG8_LDA(At, 0, 0); PG8_STAGE(PG8_SA(1, 1), a1 + hsA, voffA);
;             PG8_WAIT_V(8); PG8_WAIT_L(0); PG8_BAR; PG8_MMA(0, 0, At, B0); PG8_MMA(0, 1, At, B1); PG8_BAR; PG8_SCHED;
;             PG8_LDA(At, 0, 1); PG8_STAGE(PG8_SB(0, 0), b2, voffB); PG8_STAGE(PG8_SB(0, 1), b2 + hsB, voffB); PG8_STAGE(PG8_SA(0, 0), a2, voffA);
;             PG8_WAIT_V(8); PG8_WAIT_L(0); PG8_BAR; PG8_MMA(1, 0, At, B0); PG8_MMA(1, 1, At, B1); PG8_BAR; PG8_SCHED;
.LBB0_64:
	ds_read_b128 v[128:131], v158
	ds_read_b128 v[150:153], v251
	ds_read_b128 v[166:169], v158 offset:2048
	ds_read_b128 v[170:173], v251 offset:2048
	ds_read_b128 v[174:177], v159
	ds_read_b128 v[178:181], v252
	ds_read_b128 v[182:185], v159 offset:2048
	ds_read_b128 v[186:189], v252 offset:2048
	s_add_u32 s6, s4, 0xffefc080
	s_addc_u32 s7, s5, -1
	s_cmp_eq_u32 s91, 60
	s_cselect_b32 s63, s59, s7
	s_cselect_b32 s62, s58, s6
	s_cselect_b32 s7, s61, s90
	s_cselect_b32 s6, s60, s89
	s_sub_u32 s100, s4, 0x104000
	s_subb_u32 s101, s5, 0
	v_lshl_add_u64 v[242:243], s[100:101], 0, v[132:133]
	s_mov_b32 m0, s76
	v_lshl_add_u64 v[244:245], s[100:101], 0, v[136:137]
	global_load_lds_dwordx4 v[242:243], off
	s_mov_b32 m0, s77
	s_nop 0
	global_load_lds_dwordx4 v[244:245], off
	v_lshl_add_u64 v[226:227], s[4:5], 0, v[142:143]
	s_add_i32 m0, s68, 0xc000
	ds_read_b128 v[190:193], v160
	ds_read_b128 v[194:197], v250
	ds_read_b128 v[198:201], v160 offset:2048
	ds_read_b128 v[206:209], v250 offset:2048
	ds_read_b128 v[210:213], v160 offset:4096
	ds_read_b128 v[214:217], v250 offset:4096
	ds_read_b128 v[218:221], v160 offset:6144
	ds_read_b128 v[222:225], v250 offset:6144
	global_load_lds_dwordx4 v[226:227], off
	v_lshl_add_u64 v[226:227], s[4:5], 0, v[144:145]
	s_add_i32 m0, s68, 0xe000
	s_nop 0
	global_load_lds_dwordx4 v[226:227], off
	s_waitcnt vmcnt(8)
	s_waitcnt lgkmcnt(0)
	s_barrier
	s_setprio 3
	s_waitcnt lgkmcnt(0)
	v_mfma_f32_16x16x32_bf16 v[124:127], v[128:131], v[190:193], v[124:127]
	v_mfma_f32_16x16x32_bf16 v[124:127], v[150:153], v[194:197], v[124:127]
	v_mfma_f32_16x16x32_bf16 v[120:123], v[166:169], v[190:193], v[120:123]
	v_mfma_f32_16x16x32_bf16 v[120:123], v[170:173], v[194:197], v[120:123]
	v_mfma_f32_16x16x32_bf16 v[108:111], v[128:131], v[198:201], v[108:111]
	v_mfma_f32_16x16x32_bf16 v[108:111], v[150:153], v[206:209], v[108:111]
	v_mfma_f32_16x16x32_bf16 v[104:107], v[166:169], v[198:201], v[104:107]
	v_mfma_f32_16x16x32_bf16 v[104:107], v[170:173], v[206:209], v[104:107]
	v_mfma_f32_16x16x32_bf16 v[92:95], v[128:131], v[210:213], v[92:95]
	v_mfma_f32_16x16x32_bf16 v[92:95], v[150:153], v[214:217], v[92:95]
	v_mfma_f32_16x16x32_bf16 v[88:91], v[166:169], v[210:213], v[88:91]
	v_mfma_f32_16x16x32_bf16 v[88:91], v[170:173], v[214:217], v[88:91]
	v_mfma_f32_16x16x32_bf16 v[76:79], v[128:131], v[218:221], v[76:79]
	v_mfma_f32_16x16x32_bf16 v[76:79], v[150:153], v[222:225], v[76:79]
	v_mfma_f32_16x16x32_bf16 v[72:75], v[166:169], v[218:221], v[72:75]
	v_mfma_f32_16x16x32_bf16 v[72:75], v[170:173], v[222:225], v[72:75]
	s_setprio 0
	s_setprio 3
	v_mfma_f32_16x16x32_bf16 v[116:119], v[174:177], v[190:193], v[116:119]
	v_mfma_f32_16x16x32_bf16 v[116:119], v[178:181], v[194:197], v[116:119]
	v_mfma_f32_16x16x32_bf16 v[112:115], v[182:185], v[190:193], v[112:115]
	v_mfma_f32_16x16x32_bf16 v[112:115], v[186:189], v[194:197], v[112:115]
	v_mfma_f32_16x16x32_bf16 v[100:103], v[174:177], v[198:201], v[100:103]
	v_mfma_f32_16x16x32_bf16 v[100:103], v[178:181], v[206:209], v[100:103]
	v_mfma_f32_16x16x32_bf16 v[96:99], v[182:185], v[198:201], v[96:99]
	v_mfma_f32_16x16x32_bf16 v[96:99], v[186:189], v[206:209], v[96:99]
	v_mfma_f32_16x16x32_bf16 v[84:87], v[174:177], v[210:213], v[84:87]
	v_mfma_f32_16x16x32_bf16 v[84:87], v[178:181], v[214:217], v[84:87]
	v_mfma_f32_16x16x32_bf16 v[80:83], v[182:185], v[210:213], v[80:83]
	v_mfma_f32_16x16x32_bf16 v[80:83], v[186:189], v[214:217], v[80:83]
	v_mfma_f32_16x16x32_bf16 v[68:71], v[174:177], v[218:221], v[68:71]
	v_mfma_f32_16x16x32_bf16 v[68:71], v[178:181], v[222:225], v[68:71]
	v_mfma_f32_16x16x32_bf16 v[64:67], v[182:185], v[218:221], v[64:67]
	v_mfma_f32_16x16x32_bf16 v[64:67], v[186:189], v[222:225], v[64:67]
	s_setprio 0
	s_barrier
	s_add_i32 s92, s82, s67
	v_lshl_add_u64 v[226:227], s[6:7], 0, v[134:135]
	s_mov_b32 m0, s92
	ds_read_b128 v[190:193], v160 offset:16384
	ds_read_b128 v[194:197], v250 offset:16384
	ds_read_b128 v[198:201], v160 offset:18432
	ds_read_b128 v[206:209], v250 offset:18432
	ds_read_b128 v[210:213], v160 offset:20480
	ds_read_b128 v[214:217], v250 offset:20480
	ds_read_b128 v[218:221], v160 offset:22528
	ds_read_b128 v[222:225], v250 offset:22528
	global_load_lds_dwordx4 v[226:227], off
	s_add_i32 m0, s92, 0x2000
	s_add_u32 s92, s6, 0x41000
	v_lshl_add_u64 v[228:229], s[6:7], 0, v[138:139]
	s_addc_u32 s93, s7, 0
	s_add_i32 s94, s83, s67
	global_load_lds_dwordx4 v[228:229], off
	v_lshl_add_u64 v[230:231], s[92:93], 0, v[134:135]
	s_mov_b32 m0, s94
	s_nop 0
	global_load_lds_dwordx4 v[230:231], off
	v_lshl_add_u64 v[230:231], s[92:93], 0, v[138:139]
	s_add_i32 m0, s94, 0x2000
	s_nop 0
	global_load_lds_dwordx4 v[230:231], off
	s_waitcnt vmcnt(6)
	s_waitcnt lgkmcnt(0)
	s_barrier
; #define PG8_STAGE(bufoff, gbase, voff) do { _Pragma("unroll") for (int _i = 0; _i < 2; ++_i) \
;         __builtin_amdgcn_global_load_lds((const unsigned*)((const char*)(gbase) + (voff)[_i]), (LAS unsigned*)(lds + (bufoff) + ldsw + _i * 8192), 16, 0, 0); } while (0)
; #define PG8_LDA(dst, b, h) do { _Pragma("unroll") for (int m = 0; m < 4; ++m) _Pragma("unroll") for (int k = 0; k < 2; ++k) dst[m][k] = *(const LAS bf16x8*)(lds + PG8_SA(b, h) + aoff + m * 2048 + k * 1024); } while (0)
; #define PG8_LDB(dst, b, h) do { _Pragma("unroll") for (int n = 0; n < 2; ++n) _Pragma("unroll") for (int k = 0; k < 2; ++k) dst[n][k] = *(const LAS bf16x8*)(lds + PG8_SB(b, h) + boff + n * 2048 + k * 1024); } while (0)
; #define PG8_MMA(ai, bj, At, Bt) do { __builtin_amdgcn_s_setprio(3); _Pragma("unroll") for (int m = 0; m < 4; ++m) _Pragma("unroll") for (int n = 0; n < 2; ++n) _Pragma("unroll") for (int k = 0; k < 2; ++k) \
;         acc[ai][bj][m][n] = __builtin_amdgcn_mfma_f32_16x16x32_bf16(Bt[n][k], At[m][k], acc[ai][bj][m][n], 0, 0, 0); __builtin_amdgcn_s_setprio(0); } while (0)
; #define PG8_WAIT_V(n) asm volatile("s_waitcnt vmcnt(" #n ")" ::: "memory")
; #define PG8_WAIT_L(n) asm volatile("s_waitcnt lgkmcnt(" #n ")" ::: "memory")
; #define PG8_BAR __builtin_amdgcn_s_barrier()
; #define PG8_SCHED __builtin_amdgcn_sched_barrier(0)
; template <class Epi, class Sched, bool ALIGN_EPI = false, bool SP2 = false>
; __device__ __forceinline__ void gemm_phase(LAS unsigned char* lds, const Gemm g, const Sched& S, const Epi& E) {
;     ...
;             PG8_WAIT_V(8); PG8_WAIT_L(0); PG8_BAR; PG8_MMA(1, 0, At, B0); PG8_MMA(1, 1, At, B1); PG8_BAR; PG8_SCHED;
;             PG8_LDB(B0, 1, 0); PG8_LDB(B1, 1, 1); PG8_SCHED; PG8_LDA(At, 1, 0); PG8_STAGE(PG8_SA(0, 1), a2 + hsA, voffA);
;             PG8_WAIT_V(8); PG8_WAIT_L(0); PG8_BAR; PG8_MMA(0, 0, At, B0); PG8_MMA(0, 1, At, B1); PG8_BAR; PG8_SCHED;
	s_setprio 3
	s_waitcnt lgkmcnt(0)
	v_mfma_f32_16x16x32_bf16 v[60:63], v[128:131], v[190:193], v[60:63]
	v_mfma_f32_16x16x32_bf16 v[60:63], v[150:153], v[194:197], v[60:63]
	v_mfma_f32_16x16x32_bf16 v[56:59], v[166:169], v[190:193], v[56:59]
	v_mfma_f32_16x16x32_bf16 v[56:59], v[170:173], v[194:197], v[56:59]
	v_mfma_f32_16x16x32_bf16 v[44:47], v[128:131], v[198:201], v[44:47]
	v_mfma_f32_16x16x32_bf16 v[44:47], v[150:153], v[206:209], v[44:47]
	v_mfma_f32_16x16x32_bf16 v[40:43], v[166:169], v[198:201], v[40:43]
	v_mfma_f32_16x16x32_bf16 v[40:43], v[170:173], v[206:209], v[40:43]
	v_mfma_f32_16x16x32_bf16 v[28:31], v[128:131], v[210:213], v[28:31]
	v_mfma_f32_16x16x32_bf16 v[28:31], v[150:153], v[214:217], v[28:31]
	v_mfma_f32_16x16x32_bf16 v[24:27], v[166:169], v[210:213], v[24:27]
	v_mfma_f32_16x16x32_bf16 v[24:27], v[170:173], v[214:217], v[24:27]
	v_mfma_f32_16x16x32_bf16 v[12:15], v[128:131], v[218:221], v[12:15]
	v_mfma_f32_16x16x32_bf16 v[12:15], v[150:153], v[222:225], v[12:15]
	v_mfma_f32_16x16x32_bf16 v[8:11], v[166:169], v[218:221], v[8:11]
	v_mfma_f32_16x16x32_bf16 v[8:11], v[170:173], v[222:225], v[8:11]
	s_setprio 0
	s_setprio 3
	v_mfma_f32_16x16x32_bf16 v[52:55], v[174:177], v[190:193], v[52:55]
	v_mfma_f32_16x16x32_bf16 v[52:55], v[178:181], v[194:197], v[52:55]
	v_mfma_f32_16x16x32_bf16 v[48:51], v[182:185], v[190:193], v[48:51]
	v_mfma_f32_16x16x32_bf16 v[48:51], v[186:189], v[194:197], v[48:51]
	v_mfma_f32_16x16x32_bf16 v[36:39], v[174:177], v[198:201], v[36:39]
	v_mfma_f32_16x16x32_bf16 v[36:39], v[178:181], v[206:209], v[36:39]
	v_mfma_f32_16x16x32_bf16 v[32:35], v[182:185], v[198:201], v[32:35]
	v_mfma_f32_16x16x32_bf16 v[32:35], v[186:189], v[206:209], v[32:35]
	v_mfma_f32_16x16x32_bf16 v[20:23], v[174:177], v[210:213], v[20:23]
	v_mfma_f32_16x16x32_bf16 v[20:23], v[178:181], v[214:217], v[20:23]
	v_mfma_f32_16x16x32_bf16 v[16:19], v[182:185], v[210:213], v[16:19]
	v_mfma_f32_16x16x32_bf16 v[16:19], v[186:189], v[214:217], v[16:19]
	v_mfma_f32_16x16x32_bf16 v[4:7], v[174:177], v[218:221], v[4:7]
	v_mfma_f32_16x16x32_bf16 v[4:7], v[178:181], v[222:225], v[4:7]
	v_mfma_f32_16x16x32_bf16 v[0:3], v[182:185], v[218:221], v[0:3]
	v_mfma_f32_16x16x32_bf16 v[0:3], v[186:189], v[222:225], v[0:3]
	s_setprio 0
	s_barrier
	s_add_i32 s92, 0, 0x18000
	v_add_u32_e32 v165, s92, v156
	v_xor_b32_e32 v253, 64, v165
	s_add_i32 s93, 0, 0x1c000
	ds_read_b128 v[128:131], v165
	ds_read_b128 v[150:153], v253
	ds_read_b128 v[166:169], v165 offset:2048
	ds_read_b128 v[170:173], v253 offset:2048
	v_add_u32_e32 v165, s93, v156
	v_xor_b32_e32 v253, 64, v165
	ds_read_b128 v[174:177], v165
	ds_read_b128 v[178:181], v253
	ds_read_b128 v[182:185], v165 offset:2048
	ds_read_b128 v[186:189], v253 offset:2048
	v_lshl_add_u64 v[242:243], s[62:63], 0, v[132:133]
	s_mov_b32 m0, s68
	v_lshl_add_u64 v[244:245], s[62:63], 0, v[136:137]
	global_load_lds_dwordx4 v[242:243], off
	s_mov_b32 m0, s69
	s_nop 0
	global_load_lds_dwordx4 v[244:245], off
	s_add_u32 s62, s62, 0x104000
	s_addc_u32 s63, s63, 0
	s_mov_b32 m0, s70
	v_lshl_add_u64 v[234:235], s[62:63], 0, v[132:133]
	ds_read_b128 v[190:193], v160 offset:32768
	ds_read_b128 v[194:197], v250 offset:32768
	ds_read_b128 v[198:201], v160 offset:34816
	ds_read_b128 v[206:209], v250 offset:34816
	ds_read_b128 v[210:213], v160 offset:36864
	ds_read_b128 v[214:217], v250 offset:36864
	ds_read_b128 v[218:221], v160 offset:38912
	ds_read_b128 v[222:225], v250 offset:38912
	global_load_lds_dwordx4 v[234:235], off
	v_lshl_add_u64 v[234:235], s[62:63], 0, v[136:137]
	s_mov_b32 m0, s71
	s_nop 0
	global_load_lds_dwordx4 v[234:235], off
	s_waitcnt vmcnt(8)
	s_waitcnt lgkmcnt(0)
	s_barrier
; #define PG8_STAGE(bufoff, gbase, voff) do { _Pragma("unroll") for (int _i = 0; _i < 2; ++_i) \
;         __builtin_amdgcn_global_load_lds((const unsigned*)((const char*)(gbase) + (voff)[_i]), (LAS unsigned*)(lds + (bufoff) + ldsw + _i * 8192), 16, 0, 0); } while (0)
; #define PG8_LDA(dst, b, h) do { _Pragma("unroll") for (int m = 0; m < 4; ++m) _Pragma("unroll") for (int k = 0; k < 2; ++k) dst[m][k] = *(const LAS bf16x8*)(lds + PG8_SA(b, h) + aoff + m * 2048 + k * 1024); } while (0)
; #define PG8_MMA(ai, bj, At, Bt) do { __builtin_amdgcn_s_setprio(3); _Pragma("unroll") for (int m = 0; m < 4; ++m) _Pragma("unroll") for (int n = 0; n < 2; ++n) _Pragma("unroll") for (int k = 0; k < 2; ++k) \
;         acc[ai][bj][m][n] = __builtin_amdgcn_mfma_f32_16x16x32_bf16(Bt[n][k], At[m][k], acc[ai][bj][m][n], 0, 0, 0); __builtin_amdgcn_s_setprio(0); } while (0)
; #define PG8_WAIT_V(n) asm volatile("s_waitcnt vmcnt(" #n ")" ::: "memory")
; #define PG8_WAIT_L(n) asm volatile("s_waitcnt lgkmcnt(" #n ")" ::: "memory")
; #define PG8_BAR __builtin_amdgcn_s_barrier()
; #define PG8_SCHED __builtin_amdgcn_sched_barrier(0)
; template <class Epi, class Sched, bool ALIGN_EPI = false, bool SP2 = false>
; __device__ __forceinline__ void gemm_phase(LAS unsigned char* lds, const Gemm g, const Sched& S, const Epi& E) {
;     ...
;             PG8_WAIT_V(8); PG8_WAIT_L(0); PG8_BAR; PG8_MMA(0, 0, At, B0); PG8_MMA(0, 1, At, B1); PG8_BAR; PG8_SCHED;
;             PG8_LDA(At, 1, 1); PG8_STAGE(PG8_SB(1, 0), b3, voffB); PG8_STAGE(PG8_SB(1, 1), b3 + hsB, voffB); PG8_STAGE(PG8_SA(1, 0), a3, voffA);
;             PG8_WAIT_V(8); PG8_WAIT_L(0); PG8_BAR; PG8_MMA(1, 0, At, B0); PG8_MMA(1, 1, At, B1); PG8_BAR; PG8_SCHED;
	s_setprio 3
	s_waitcnt lgkmcnt(0)
	v_mfma_f32_16x16x32_bf16 v[124:127], v[128:131], v[190:193], v[124:127]
	v_mfma_f32_16x16x32_bf16 v[124:127], v[150:153], v[194:197], v[124:127]
	v_mfma_f32_16x16x32_bf16 v[120:123], v[166:169], v[190:193], v[120:123]
	v_mfma_f32_16x16x32_bf16 v[120:123], v[170:173], v[194:197], v[120:123]
	v_mfma_f32_16x16x32_bf16 v[108:111], v[128:131], v[198:201], v[108:111]
	v_mfma_f32_16x16x32_bf16 v[108:111], v[150:153], v[206:209], v[108:111]
	v_mfma_f32_16x16x32_bf16 v[104:107], v[166:169], v[198:201], v[104:107]
	v_mfma_f32_16x16x32_bf16 v[104:107], v[170:173], v[206:209], v[104:107]
	v_mfma_f32_16x16x32_bf16 v[92:95], v[128:131], v[210:213], v[92:95]
	v_mfma_f32_16x16x32_bf16 v[92:95], v[150:153], v[214:217], v[92:95]
	v_mfma_f32_16x16x32_bf16 v[88:91], v[166:169], v[210:213], v[88:91]
	v_mfma_f32_16x16x32_bf16 v[88:91], v[170:173], v[214:217], v[88:91]
	v_mfma_f32_16x16x32_bf16 v[76:79], v[128:131], v[218:221], v[76:79]
	v_mfma_f32_16x16x32_bf16 v[76:79], v[150:153], v[222:225], v[76:79]
	v_mfma_f32_16x16x32_bf16 v[72:75], v[166:169], v[218:221], v[72:75]
	v_mfma_f32_16x16x32_bf16 v[72:75], v[170:173], v[222:225], v[72:75]
	s_setprio 0
	s_setprio 3
	v_mfma_f32_16x16x32_bf16 v[116:119], v[174:177], v[190:193], v[116:119]
	v_mfma_f32_16x16x32_bf16 v[116:119], v[178:181], v[194:197], v[116:119]
	v_mfma_f32_16x16x32_bf16 v[112:115], v[182:185], v[190:193], v[112:115]
	v_mfma_f32_16x16x32_bf16 v[112:115], v[186:189], v[194:197], v[112:115]
	v_mfma_f32_16x16x32_bf16 v[100:103], v[174:177], v[198:201], v[100:103]
	v_mfma_f32_16x16x32_bf16 v[100:103], v[178:181], v[206:209], v[100:103]
	v_mfma_f32_16x16x32_bf16 v[96:99], v[182:185], v[198:201], v[96:99]
	v_mfma_f32_16x16x32_bf16 v[96:99], v[186:189], v[206:209], v[96:99]
	v_mfma_f32_16x16x32_bf16 v[84:87], v[174:177], v[210:213], v[84:87]
	v_mfma_f32_16x16x32_bf16 v[84:87], v[178:181], v[214:217], v[84:87]
	v_mfma_f32_16x16x32_bf16 v[80:83], v[182:185], v[210:213], v[80:83]
	v_mfma_f32_16x16x32_bf16 v[80:83], v[186:189], v[214:217], v[80:83]
	v_mfma_f32_16x16x32_bf16 v[68:71], v[174:177], v[218:221], v[68:71]
	v_mfma_f32_16x16x32_bf16 v[68:71], v[178:181], v[222:225], v[68:71]
	v_mfma_f32_16x16x32_bf16 v[64:67], v[182:185], v[218:221], v[64:67]
	v_mfma_f32_16x16x32_bf16 v[64:67], v[186:189], v[222:225], v[64:67]
	s_setprio 0
	s_barrier
	s_add_i32 s62, s92, s67
	v_lshl_add_u64 v[226:227], v[226:227], 0, s[46:47]
	s_mov_b32 m0, s62
	ds_read_b128 v[190:193], v160 offset:49152
	ds_read_b128 v[194:197], v250 offset:49152
	ds_read_b128 v[198:201], v160 offset:51200
	ds_read_b128 v[206:209], v250 offset:51200
	ds_read_b128 v[210:213], v160 offset:53248
	ds_read_b128 v[214:217], v250 offset:53248
	ds_read_b128 v[218:221], v160 offset:55296
	ds_read_b128 v[222:225], v250 offset:55296
	global_load_lds_dwordx4 v[226:227], off
	s_add_i32 m0, s62, 0x2000
	s_add_u32 s6, s6, 0x41080
	v_lshl_add_u64 v[226:227], v[228:229], 0, s[46:47]
	s_addc_u32 s7, s7, 0
	s_add_i32 s62, s93, s67
	global_load_lds_dwordx4 v[226:227], off
	v_lshl_add_u64 v[226:227], s[6:7], 0, v[134:135]
	s_mov_b32 m0, s62
	s_nop 0
	global_load_lds_dwordx4 v[226:227], off
	v_lshl_add_u64 v[226:227], s[6:7], 0, v[138:139]
	s_add_i32 m0, s62, 0x2000
	s_nop 0
	global_load_lds_dwordx4 v[226:227], off
	s_waitcnt vmcnt(6)
	s_waitcnt lgkmcnt(0)
	s_barrier
	s_setprio 3
	s_waitcnt lgkmcnt(0)
	v_mfma_f32_16x16x32_bf16 v[60:63], v[128:131], v[190:193], v[60:63]
	v_mfma_f32_16x16x32_bf16 v[60:63], v[150:153], v[194:197], v[60:63]
	v_mfma_f32_16x16x32_bf16 v[56:59], v[166:169], v[190:193], v[56:59]
	v_mfma_f32_16x16x32_bf16 v[56:59], v[170:173], v[194:197], v[56:59]
	v_mfma_f32_16x16x32_bf16 v[44:47], v[128:131], v[198:201], v[44:47]
	v_mfma_f32_16x16x32_bf16 v[44:47], v[150:153], v[206:209], v[44:47]
	v_mfma_f32_16x16x32_bf16 v[40:43], v[166:169], v[198:201], v[40:43]
	v_mfma_f32_16x16x32_bf16 v[40:43], v[170:173], v[206:209], v[40:43]
	v_mfma_f32_16x16x32_bf16 v[28:31], v[128:131], v[210:213], v[28:31]
	v_mfma_f32_16x16x32_bf16 v[28:31], v[150:153], v[214:217], v[28:31]
	v_mfma_f32_16x16x32_bf16 v[24:27], v[166:169], v[210:213], v[24:27]
	v_mfma_f32_16x16x32_bf16 v[24:27], v[170:173], v[214:217], v[24:27]
	v_mfma_f32_16x16x32_bf16 v[12:15], v[128:131], v[218:221], v[12:15]
	v_mfma_f32_16x16x32_bf16 v[12:15], v[150:153], v[222:225], v[12:15]
	v_mfma_f32_16x16x32_bf16 v[8:11], v[166:169], v[218:221], v[8:11]
	v_mfma_f32_16x16x32_bf16 v[8:11], v[170:173], v[222:225], v[8:11]
	s_setprio 0
	s_setprio 3
	v_mfma_f32_16x16x32_bf16 v[52:55], v[174:177], v[190:193], v[52:55]
	v_mfma_f32_16x16x32_bf16 v[52:55], v[178:181], v[194:197], v[52:55]
	v_mfma_f32_16x16x32_bf16 v[48:51], v[182:185], v[190:193], v[48:51]
	v_mfma_f32_16x16x32_bf16 v[48:51], v[186:189], v[194:197], v[48:51]
	v_mfma_f32_16x16x32_bf16 v[36:39], v[174:177], v[198:201], v[36:39]
	v_mfma_f32_16x16x32_bf16 v[36:39], v[178:181], v[206:209], v[36:39]
	v_mfma_f32_16x16x32_bf16 v[32:35], v[182:185], v[198:201], v[32:35]
	v_mfma_f32_16x16x32_bf16 v[32:35], v[186:189], v[206:209], v[32:35]
	v_mfma_f32_16x16x32_bf16 v[20:23], v[174:177], v[210:213], v[20:23]
	v_mfma_f32_16x16x32_bf16 v[20:23], v[178:181], v[214:217], v[20:23]
	v_mfma_f32_16x16x32_bf16 v[16:19], v[182:185], v[210:213], v[16:19]
	v_mfma_f32_16x16x32_bf16 v[16:19], v[186:189], v[214:217], v[16:19]
	v_mfma_f32_16x16x32_bf16 v[4:7], v[174:177], v[218:221], v[4:7]
	v_mfma_f32_16x16x32_bf16 v[4:7], v[178:181], v[222:225], v[4:7]
	v_mfma_f32_16x16x32_bf16 v[0:3], v[182:185], v[218:221], v[0:3]
	v_mfma_f32_16x16x32_bf16 v[0:3], v[186:189], v[222:225], v[0:3]
	s_setprio 0
	s_barrier
	s_add_i32 s91, s91, 2
	s_add_u32 s4, s4, 0x100
	s_addc_u32 s5, s5, 0
	s_add_u32 s89, s89, 0x100
	s_addc_u32 s90, s90, 0
	s_cmp_gt_u32 s91, 61
	s_cbranch_scc0 .LBB0_64
	s_and_b64 vcc, exec, s[50:51]
	s_cbranch_vccz .LBB0_67
	s_barrier

; #define PG8_STAGE(bufoff, gbase, voff) do { _Pragma("unroll") for (int _i = 0; _i < 2; ++_i) \
;         __builtin_amdgcn_global_load_lds((const unsigned*)((const char*)(gbase) + (voff)[_i]), (LAS unsigned*)(lds + (bufoff) + ldsw + _i * 8192), 16, 0, 0); } while (0)
; #define PG8_LDA(dst, b, h) do { _Pragma("unroll") for (int m = 0; m < 4; ++m) _Pragma("unroll") for (int k = 0; k < 2; ++k) dst[m][k] = *(const LAS bf16x8*)(lds + PG8_SA(b, h) + aoff + m * 2048 + k * 1024); } while (0)
; #define PG8_LDB(dst, b, h) do { _Pragma("unroll") for (int n = 0; n < 2; ++n) _Pragma("unroll") for (int k = 0; k < 2; ++k) dst[n][k] = *(const LAS bf16x8*)(lds + PG8_SB(b, h) + boff + n * 2048 + k * 1024); } while (0)
; #define PG8_MMA(ai, bj, At, Bt) do { __builtin_amdgcn_s_setprio(3); _Pragma("unroll") for (int m = 0; m < 4; ++m) _Pragma("unroll") for (int n = 0; n < 2; ++n) _Pragma("unroll") for (int k = 0; k < 2; ++k) \
;         acc[ai][bj][m][n] = __builtin_amdgcn_mfma_f32_16x16x32_bf16(Bt[n][k], At[m][k], acc[ai][bj][m][n], 0, 0, 0); __builtin_amdgcn_s_setprio(0); } while (0)
; #define PG8_WAIT_V(n) asm volatile("s_waitcnt vmcnt(" #n ")" ::: "memory")
; #define PG8_WAIT_L(n) asm volatile("s_waitcnt lgkmcnt(" #n ")" ::: "memory")
; #define PG8_BAR __builtin_amdgcn_s_barrier()
; #define PG8_SCHED __builtin_amdgcn_sched_barrier(0)
; template <class Epi, class Sched, bool ALIGN_EPI = false, bool SP2 = false>
; __device__ __forceinline__ void gemm_phase(LAS unsigned char* lds, const Gemm g, const Sched& S, const Epi& E) {
;     ...
;             PG8_LDB(B0, 0, 0); PG8_LDB(B1, 0, 1); PG8_SCHED; PG8_LDA(At, 0, 0); PG8_STAGE(PG8_SA(1, 1), a1 + hsA, voffA);
;             PG8_WAIT_V(8); PG8_WAIT_L(0); PG8_BAR; PG8_MMA(0, 0, At, B0); PG8_MMA(0, 1, At, B1); PG8_BAR; PG8_SCHED;
;             PG8_LDA(At, 0, 1); PG8_STAGE(PG8_SB(0, 0), b2, voffB); PG8_STAGE(PG8_SB(0, 1), b2 + hsB, voffB); PG8_STAGE(PG8_SA(0, 0), a2, voffA);
;             PG8_WAIT_V(8); PG8_WAIT_L(0); PG8_BAR; PG8_MMA(1, 0, At, B0); PG8_MMA(1, 1, At, B1); PG8_BAR; PG8_SCHED;
.LBB0_234:
	v_add_u32_e32 v1, s88, v194
	v_xor_b32_e32 v253, 64, v1
	ds_read_b128 v[84:87], v1
	ds_read_b128 v[96:99], v253
	ds_read_b128 v[140:143], v1 offset:2048
	ds_read_b128 v[144:147], v253 offset:2048
	v_add_u32_e32 v1, s89, v194
	v_xor_b32_e32 v253, 64, v1
	s_add_u32 s4, s64, s66
	ds_read_b128 v[152:155], v1
	ds_read_b128 v[156:159], v253
	ds_read_b128 v[160:163], v1 offset:2048
	ds_read_b128 v[182:185], v253 offset:2048
	s_addc_u32 s5, s65, s67
	s_add_u32 s4, s4, 0x100
	s_addc_u32 s5, s5, 0
	s_add_u32 s96, s93, s66
	s_addc_u32 s97, s94, s67
	s_cmpk_eq_i32 s66, 0x1f00
	s_cselect_b32 s9, s59, s5
	s_cselect_b32 s8, s91, s4
	s_cselect_b32 s5, s61, s97
	s_cselect_b32 s4, s60, s96
	s_sub_u32 s100, s66, 0x100000
	s_subb_u32 s101, s67, 0
	v_lshl_add_u64 v[242:243], v[148:149], 0, s[100:101]
	s_mov_b32 m0, s81
	v_lshl_add_u64 v[244:245], v[150:151], 0, s[100:101]
	global_load_lds_dwordx4 v[242:243], off
	s_mov_b32 m0, s82
	s_nop 0
	global_load_lds_dwordx4 v[244:245], off
	v_lshl_add_u64 v[2:3], v[148:149], 0, s[66:67]
	s_add_i32 m0, s41, 0xc000
	ds_read_b128 v[186:189], v198
	ds_read_b128 v[208:211], v250
	ds_read_b128 v[212:215], v198 offset:2048
	ds_read_b128 v[216:219], v250 offset:2048
	ds_read_b128 v[220:223], v198 offset:4096
	ds_read_b128 v[224:227], v250 offset:4096
	ds_read_b128 v[228:231], v198 offset:6144
	ds_read_b128 v[232:235], v250 offset:6144
	global_load_lds_dwordx4 v[2:3], off
	v_lshl_add_u64 v[2:3], v[150:151], 0, s[66:67]
	s_add_i32 m0, s41, 0xe000
	s_nop 0
	global_load_lds_dwordx4 v[2:3], off
	s_waitcnt vmcnt(8)
	s_waitcnt lgkmcnt(0)
	s_barrier
	s_setprio 3
	s_waitcnt lgkmcnt(0)
	v_mfma_f32_16x16x32_bf16 v[136:139], v[84:87], v[186:189], v[136:139]
	v_mfma_f32_16x16x32_bf16 v[136:139], v[96:99], v[208:211], v[136:139]
	v_mfma_f32_16x16x32_bf16 v[132:135], v[140:143], v[186:189], v[132:135]
	v_mfma_f32_16x16x32_bf16 v[132:135], v[144:147], v[208:211], v[132:135]
	v_mfma_f32_16x16x32_bf16 v[120:123], v[84:87], v[212:215], v[120:123]
	v_mfma_f32_16x16x32_bf16 v[120:123], v[96:99], v[216:219], v[120:123]
	v_mfma_f32_16x16x32_bf16 v[116:119], v[140:143], v[212:215], v[116:119]
	v_mfma_f32_16x16x32_bf16 v[116:119], v[144:147], v[216:219], v[116:119]
	v_mfma_f32_16x16x32_bf16 v[104:107], v[84:87], v[220:223], v[104:107]
	v_mfma_f32_16x16x32_bf16 v[104:107], v[96:99], v[224:227], v[104:107]
	v_mfma_f32_16x16x32_bf16 v[100:103], v[140:143], v[220:223], v[100:103]
	v_mfma_f32_16x16x32_bf16 v[100:103], v[144:147], v[224:227], v[100:103]
	v_mfma_f32_16x16x32_bf16 v[80:83], v[84:87], v[228:231], v[80:83]
	v_mfma_f32_16x16x32_bf16 v[80:83], v[96:99], v[232:235], v[80:83]
	v_mfma_f32_16x16x32_bf16 v[76:79], v[140:143], v[228:231], v[76:79]
	v_mfma_f32_16x16x32_bf16 v[76:79], v[144:147], v[232:235], v[76:79]
	s_setprio 0
	s_setprio 3
	v_mfma_f32_16x16x32_bf16 v[128:131], v[152:155], v[186:189], v[128:131]
	v_mfma_f32_16x16x32_bf16 v[128:131], v[156:159], v[208:211], v[128:131]
	v_mfma_f32_16x16x32_bf16 v[124:127], v[160:163], v[186:189], v[124:127]
	v_mfma_f32_16x16x32_bf16 v[124:127], v[182:185], v[208:211], v[124:127]
	v_mfma_f32_16x16x32_bf16 v[112:115], v[152:155], v[212:215], v[112:115]
	v_mfma_f32_16x16x32_bf16 v[112:115], v[156:159], v[216:219], v[112:115]
	v_mfma_f32_16x16x32_bf16 v[108:111], v[160:163], v[212:215], v[108:111]
	v_mfma_f32_16x16x32_bf16 v[108:111], v[182:185], v[216:219], v[108:111]
	v_mfma_f32_16x16x32_bf16 v[92:95], v[152:155], v[220:223], v[92:95]
	v_mfma_f32_16x16x32_bf16 v[92:95], v[156:159], v[224:227], v[92:95]
	v_mfma_f32_16x16x32_bf16 v[88:91], v[160:163], v[220:223], v[88:91]
	v_mfma_f32_16x16x32_bf16 v[88:91], v[182:185], v[224:227], v[88:91]
	v_mfma_f32_16x16x32_bf16 v[72:75], v[152:155], v[228:231], v[72:75]
	v_mfma_f32_16x16x32_bf16 v[72:75], v[156:159], v[232:235], v[72:75]
	v_mfma_f32_16x16x32_bf16 v[68:71], v[160:163], v[228:231], v[68:71]
	v_mfma_f32_16x16x32_bf16 v[68:71], v[182:185], v[232:235], v[68:71]
	s_setprio 0
	s_barrier
	s_add_i32 s96, s88, s31
	v_lshl_add_u64 v[190:191], s[4:5], 0, v[166:167]
	s_mov_b32 m0, s96
	ds_read_b128 v[186:189], v198 offset:16384
	ds_read_b128 v[208:211], v250 offset:16384
	ds_read_b128 v[212:215], v198 offset:18432
	ds_read_b128 v[216:219], v250 offset:18432
	ds_read_b128 v[220:223], v198 offset:20480
	ds_read_b128 v[224:227], v250 offset:20480
	ds_read_b128 v[228:231], v198 offset:22528
	ds_read_b128 v[232:235], v250 offset:22528
	global_load_lds_dwordx4 v[190:191], off
	s_add_i32 m0, s96, 0x2000
	s_add_u32 s96, s4, 0x104000
	v_lshl_add_u64 v[236:237], s[4:5], 0, v[170:171]
	s_addc_u32 s97, s5, 0
	s_add_i32 s98, s89, s31
	global_load_lds_dwordx4 v[236:237], off
	v_lshl_add_u64 v[2:3], s[96:97], 0, v[166:167]
	s_mov_b32 m0, s98
	s_nop 0
	global_load_lds_dwordx4 v[2:3], off
	v_lshl_add_u64 v[2:3], s[96:97], 0, v[170:171]
	s_add_i32 m0, s98, 0x2000
	s_nop 0
	global_load_lds_dwordx4 v[2:3], off
	s_waitcnt vmcnt(6)
	s_waitcnt lgkmcnt(0)
	s_barrier
; #define PG8_STAGE(bufoff, gbase, voff) do { _Pragma("unroll") for (int _i = 0; _i < 2; ++_i) \
;         __builtin_amdgcn_global_load_lds((const unsigned*)((const char*)(gbase) + (voff)[_i]), (LAS unsigned*)(lds + (bufoff) + ldsw + _i * 8192), 16, 0, 0); } while (0)
; #define PG8_LDA(dst, b, h) do { _Pragma("unroll") for (int m = 0; m < 4; ++m) _Pragma("unroll") for (int k = 0; k < 2; ++k) dst[m][k] = *(const LAS bf16x8*)(lds + PG8_SA(b, h) + aoff + m * 2048 + k * 1024); } while (0)
; #define PG8_LDB(dst, b, h) do { _Pragma("unroll") for (int n = 0; n < 2; ++n) _Pragma("unroll") for (int k = 0; k < 2; ++k) dst[n][k] = *(const LAS bf16x8*)(lds + PG8_SB(b, h) + boff + n * 2048 + k * 1024); } while (0)
; #define PG8_MMA(ai, bj, At, Bt) do { __builtin_amdgcn_s_setprio(3); _Pragma("unroll") for (int m = 0; m < 4; ++m) _Pragma("unroll") for (int n = 0; n < 2; ++n) _Pragma("unroll") for (int k = 0; k < 2; ++k) \
;         acc[ai][bj][m][n] = __builtin_amdgcn_mfma_f32_16x16x32_bf16(Bt[n][k], At[m][k], acc[ai][bj][m][n], 0, 0, 0); __builtin_amdgcn_s_setprio(0); } while (0)
; #define PG8_WAIT_V(n) asm volatile("s_waitcnt vmcnt(" #n ")" ::: "memory")
; #define PG8_WAIT_L(n) asm volatile("s_waitcnt lgkmcnt(" #n ")" ::: "memory")
; #define PG8_BAR __builtin_amdgcn_s_barrier()
; #define PG8_SCHED __builtin_amdgcn_sched_barrier(0)
; template <class Epi, class Sched, bool ALIGN_EPI = false, bool SP2 = false>
; __device__ __forceinline__ void gemm_phase(LAS unsigned char* lds, const Gemm g, const Sched& S, const Epi& E) {
;     ...
;             PG8_WAIT_V(8); PG8_WAIT_L(0); PG8_BAR; PG8_MMA(1, 0, At, B0); PG8_MMA(1, 1, At, B1); PG8_BAR; PG8_SCHED;
;             PG8_LDB(B0, 1, 0); PG8_LDB(B1, 1, 1); PG8_SCHED; PG8_LDA(At, 1, 0); PG8_STAGE(PG8_SA(0, 1), a2 + hsA, voffA);
;             PG8_WAIT_V(8); PG8_WAIT_L(0); PG8_BAR; PG8_MMA(0, 0, At, B0); PG8_MMA(0, 1, At, B1); PG8_BAR; PG8_SCHED;
	s_setprio 3
	s_waitcnt lgkmcnt(0)
	v_mfma_f32_16x16x32_bf16 v[64:67], v[84:87], v[186:189], v[64:67]
	v_mfma_f32_16x16x32_bf16 v[64:67], v[96:99], v[208:211], v[64:67]
	v_mfma_f32_16x16x32_bf16 v[60:63], v[140:143], v[186:189], v[60:63]
	v_mfma_f32_16x16x32_bf16 v[60:63], v[144:147], v[208:211], v[60:63]
	v_mfma_f32_16x16x32_bf16 v[48:51], v[84:87], v[212:215], v[48:51]
	v_mfma_f32_16x16x32_bf16 v[48:51], v[96:99], v[216:219], v[48:51]
	v_mfma_f32_16x16x32_bf16 v[44:47], v[140:143], v[212:215], v[44:47]
	v_mfma_f32_16x16x32_bf16 v[44:47], v[144:147], v[216:219], v[44:47]
	v_mfma_f32_16x16x32_bf16 v[32:35], v[84:87], v[220:223], v[32:35]
	v_mfma_f32_16x16x32_bf16 v[32:35], v[96:99], v[224:227], v[32:35]
	v_mfma_f32_16x16x32_bf16 v[28:31], v[140:143], v[220:223], v[28:31]
	v_mfma_f32_16x16x32_bf16 v[28:31], v[144:147], v[224:227], v[28:31]
	v_mfma_f32_16x16x32_bf16 v[16:19], v[84:87], v[228:231], v[16:19]
	v_mfma_f32_16x16x32_bf16 v[16:19], v[96:99], v[232:235], v[16:19]
	v_mfma_f32_16x16x32_bf16 v[12:15], v[140:143], v[228:231], v[12:15]
	v_mfma_f32_16x16x32_bf16 v[12:15], v[144:147], v[232:235], v[12:15]
	s_setprio 0
	s_setprio 3
	v_mfma_f32_16x16x32_bf16 v[56:59], v[152:155], v[186:189], v[56:59]
	v_mfma_f32_16x16x32_bf16 v[56:59], v[156:159], v[208:211], v[56:59]
	v_mfma_f32_16x16x32_bf16 v[52:55], v[160:163], v[186:189], v[52:55]
	v_mfma_f32_16x16x32_bf16 v[52:55], v[182:185], v[208:211], v[52:55]
	v_mfma_f32_16x16x32_bf16 v[40:43], v[152:155], v[212:215], v[40:43]
	v_mfma_f32_16x16x32_bf16 v[40:43], v[156:159], v[216:219], v[40:43]
	v_mfma_f32_16x16x32_bf16 v[36:39], v[160:163], v[212:215], v[36:39]
	v_mfma_f32_16x16x32_bf16 v[36:39], v[182:185], v[216:219], v[36:39]
	v_mfma_f32_16x16x32_bf16 v[24:27], v[152:155], v[220:223], v[24:27]
	v_mfma_f32_16x16x32_bf16 v[24:27], v[156:159], v[224:227], v[24:27]
	v_mfma_f32_16x16x32_bf16 v[20:23], v[160:163], v[220:223], v[20:23]
	v_mfma_f32_16x16x32_bf16 v[20:23], v[182:185], v[224:227], v[20:23]
	v_mfma_f32_16x16x32_bf16 v[8:11], v[152:155], v[228:231], v[8:11]
	v_mfma_f32_16x16x32_bf16 v[8:11], v[156:159], v[232:235], v[8:11]
	v_mfma_f32_16x16x32_bf16 v[2:5], v[160:163], v[228:231], v[4:7]
	v_mfma_f32_16x16x32_bf16 v[2:5], v[182:185], v[232:235], v[2:5]
	s_setprio 0
	s_barrier
	s_add_i32 s96, 0, 0x18000
	v_add_u32_e32 v1, s96, v194
	v_xor_b32_e32 v253, 64, v1
	s_add_i32 s97, 0, 0x1c000
	ds_read_b128 v[84:87], v1
	ds_read_b128 v[96:99], v253
	ds_read_b128 v[140:143], v1 offset:2048
	ds_read_b128 v[144:147], v253 offset:2048
	v_add_u32_e32 v1, s97, v194
	v_xor_b32_e32 v253, 64, v1
	ds_read_b128 v[152:155], v1
	ds_read_b128 v[156:159], v253
	ds_read_b128 v[160:163], v1 offset:2048
	ds_read_b128 v[182:185], v253 offset:2048
	v_lshl_add_u64 v[242:243], s[8:9], 0, v[164:165]
	s_mov_b32 m0, s41
	v_lshl_add_u64 v[244:245], s[8:9], 0, v[168:169]
	global_load_lds_dwordx4 v[242:243], off
	s_mov_b32 m0, s68
	s_nop 0
	global_load_lds_dwordx4 v[244:245], off
	s_add_u32 s8, s8, 0x100000
	s_addc_u32 s9, s9, 0
	s_mov_b32 m0, s69
	v_lshl_add_u64 v[6:7], s[8:9], 0, v[164:165]
	ds_read_b128 v[186:189], v198 offset:32768
	ds_read_b128 v[208:211], v250 offset:32768
	ds_read_b128 v[212:215], v198 offset:34816
	ds_read_b128 v[216:219], v250 offset:34816
	ds_read_b128 v[220:223], v198 offset:36864
	ds_read_b128 v[224:227], v250 offset:36864
	ds_read_b128 v[228:231], v198 offset:38912
	ds_read_b128 v[232:235], v250 offset:38912
	global_load_lds_dwordx4 v[6:7], off
	v_lshl_add_u64 v[6:7], s[8:9], 0, v[168:169]
	s_mov_b32 m0, s70
	s_nop 0
	global_load_lds_dwordx4 v[6:7], off
	s_waitcnt vmcnt(8)
	s_waitcnt lgkmcnt(0)
	s_barrier
; #define PG8_STAGE(bufoff, gbase, voff) do { _Pragma("unroll") for (int _i = 0; _i < 2; ++_i) \
;         __builtin_amdgcn_global_load_lds((const unsigned*)((const char*)(gbase) + (voff)[_i]), (LAS unsigned*)(lds + (bufoff) + ldsw + _i * 8192), 16, 0, 0); } while (0)
; #define PG8_LDA(dst, b, h) do { _Pragma("unroll") for (int m = 0; m < 4; ++m) _Pragma("unroll") for (int k = 0; k < 2; ++k) dst[m][k] = *(const LAS bf16x8*)(lds + PG8_SA(b, h) + aoff + m * 2048 + k * 1024); } while (0)
; #define PG8_MMA(ai, bj, At, Bt) do { __builtin_amdgcn_s_setprio(3); _Pragma("unroll") for (int m = 0; m < 4; ++m) _Pragma("unroll") for (int n = 0; n < 2; ++n) _Pragma("unroll") for (int k = 0; k < 2; ++k) \
;         acc[ai][bj][m][n] = __builtin_amdgcn_mfma_f32_16x16x32_bf16(Bt[n][k], At[m][k], acc[ai][bj][m][n], 0, 0, 0); __builtin_amdgcn_s_setprio(0); } while (0)
; #define PG8_WAIT_V(n) asm volatile("s_waitcnt vmcnt(" #n ")" ::: "memory")
; #define PG8_WAIT_L(n) asm volatile("s_waitcnt lgkmcnt(" #n ")" ::: "memory")
; #define PG8_BAR __builtin_amdgcn_s_barrier()
; #define PG8_SCHED __builtin_amdgcn_sched_barrier(0)
; template <class Epi, class Sched, bool ALIGN_EPI = false, bool SP2 = false>
; __device__ __forceinline__ void gemm_phase(LAS unsigned char* lds, const Gemm g, const Sched& S, const Epi& E) {
;     ...
;             PG8_WAIT_V(8); PG8_WAIT_L(0); PG8_BAR; PG8_MMA(0, 0, At, B0); PG8_MMA(0, 1, At, B1); PG8_BAR; PG8_SCHED;
;             PG8_LDA(At, 1, 1); PG8_STAGE(PG8_SB(1, 0), b3, voffB); PG8_STAGE(PG8_SB(1, 1), b3 + hsB, voffB); PG8_STAGE(PG8_SA(1, 0), a3, voffA);
;             PG8_WAIT_V(8); PG8_WAIT_L(0); PG8_BAR; PG8_MMA(1, 0, At, B0); PG8_MMA(1, 1, At, B1); PG8_BAR; PG8_SCHED;
	s_setprio 3
	s_waitcnt lgkmcnt(0)
	v_mfma_f32_16x16x32_bf16 v[136:139], v[84:87], v[186:189], v[136:139]
	v_mfma_f32_16x16x32_bf16 v[136:139], v[96:99], v[208:211], v[136:139]
	v_mfma_f32_16x16x32_bf16 v[132:135], v[140:143], v[186:189], v[132:135]
	v_mfma_f32_16x16x32_bf16 v[132:135], v[144:147], v[208:211], v[132:135]
	v_mfma_f32_16x16x32_bf16 v[120:123], v[84:87], v[212:215], v[120:123]
	v_mfma_f32_16x16x32_bf16 v[120:123], v[96:99], v[216:219], v[120:123]
	v_mfma_f32_16x16x32_bf16 v[116:119], v[140:143], v[212:215], v[116:119]
	v_mfma_f32_16x16x32_bf16 v[116:119], v[144:147], v[216:219], v[116:119]
	v_mfma_f32_16x16x32_bf16 v[104:107], v[84:87], v[220:223], v[104:107]
	v_mfma_f32_16x16x32_bf16 v[104:107], v[96:99], v[224:227], v[104:107]
	v_mfma_f32_16x16x32_bf16 v[100:103], v[140:143], v[220:223], v[100:103]
	v_mfma_f32_16x16x32_bf16 v[100:103], v[144:147], v[224:227], v[100:103]
	v_mfma_f32_16x16x32_bf16 v[80:83], v[84:87], v[228:231], v[80:83]
	v_mfma_f32_16x16x32_bf16 v[80:83], v[96:99], v[232:235], v[80:83]
	v_mfma_f32_16x16x32_bf16 v[76:79], v[140:143], v[228:231], v[76:79]
	v_mfma_f32_16x16x32_bf16 v[76:79], v[144:147], v[232:235], v[76:79]
	s_setprio 0
	s_setprio 3
	v_mfma_f32_16x16x32_bf16 v[128:131], v[152:155], v[186:189], v[128:131]
	v_mfma_f32_16x16x32_bf16 v[128:131], v[156:159], v[208:211], v[128:131]
	v_mfma_f32_16x16x32_bf16 v[124:127], v[160:163], v[186:189], v[124:127]
	v_mfma_f32_16x16x32_bf16 v[124:127], v[182:185], v[208:211], v[124:127]
	v_mfma_f32_16x16x32_bf16 v[112:115], v[152:155], v[212:215], v[112:115]
	v_mfma_f32_16x16x32_bf16 v[112:115], v[156:159], v[216:219], v[112:115]
	v_mfma_f32_16x16x32_bf16 v[108:111], v[160:163], v[212:215], v[108:111]
	v_mfma_f32_16x16x32_bf16 v[108:111], v[182:185], v[216:219], v[108:111]
	v_mfma_f32_16x16x32_bf16 v[92:95], v[152:155], v[220:223], v[92:95]
	v_mfma_f32_16x16x32_bf16 v[92:95], v[156:159], v[224:227], v[92:95]
	v_mfma_f32_16x16x32_bf16 v[88:91], v[160:163], v[220:223], v[88:91]
	v_mfma_f32_16x16x32_bf16 v[88:91], v[182:185], v[224:227], v[88:91]
	v_mfma_f32_16x16x32_bf16 v[72:75], v[152:155], v[228:231], v[72:75]
	v_mfma_f32_16x16x32_bf16 v[72:75], v[156:159], v[232:235], v[72:75]
	v_mfma_f32_16x16x32_bf16 v[68:71], v[160:163], v[228:231], v[68:71]
	v_mfma_f32_16x16x32_bf16 v[68:71], v[182:185], v[232:235], v[68:71]
	s_setprio 0
	s_barrier
	s_add_i32 s8, s96, s31
	v_lshl_add_u64 v[6:7], v[190:191], 0, s[24:25]
	s_mov_b32 m0, s8
	ds_read_b128 v[186:189], v198 offset:49152
	ds_read_b128 v[208:211], v250 offset:49152
	ds_read_b128 v[212:215], v198 offset:51200
	ds_read_b128 v[216:219], v250 offset:51200
	ds_read_b128 v[220:223], v198 offset:53248
	ds_read_b128 v[224:227], v250 offset:53248
	ds_read_b128 v[228:231], v198 offset:55296
	ds_read_b128 v[232:235], v250 offset:55296
	global_load_lds_dwordx4 v[6:7], off
	s_add_i32 m0, s8, 0x2000
	s_add_u32 s4, s4, 0x104080
	v_lshl_add_u64 v[6:7], v[236:237], 0, s[24:25]
	s_addc_u32 s5, s5, 0
	s_add_i32 s8, s97, s31
	global_load_lds_dwordx4 v[6:7], off
	v_lshl_add_u64 v[6:7], s[4:5], 0, v[166:167]
	s_mov_b32 m0, s8
	s_nop 0
	global_load_lds_dwordx4 v[6:7], off
	v_lshl_add_u64 v[6:7], s[4:5], 0, v[170:171]
	s_add_i32 m0, s8, 0x2000
	s_nop 0
	global_load_lds_dwordx4 v[6:7], off
	s_waitcnt vmcnt(6)
	s_waitcnt lgkmcnt(0)
	s_barrier
	s_setprio 3
	s_waitcnt lgkmcnt(0)
	v_mfma_f32_16x16x32_bf16 v[64:67], v[84:87], v[186:189], v[64:67]
	v_mfma_f32_16x16x32_bf16 v[64:67], v[96:99], v[208:211], v[64:67]
	v_mfma_f32_16x16x32_bf16 v[60:63], v[140:143], v[186:189], v[60:63]
	v_mfma_f32_16x16x32_bf16 v[60:63], v[144:147], v[208:211], v[60:63]
	v_mfma_f32_16x16x32_bf16 v[48:51], v[84:87], v[212:215], v[48:51]
	v_mfma_f32_16x16x32_bf16 v[48:51], v[96:99], v[216:219], v[48:51]
	v_mfma_f32_16x16x32_bf16 v[44:47], v[140:143], v[212:215], v[44:47]
	v_mfma_f32_16x16x32_bf16 v[44:47], v[144:147], v[216:219], v[44:47]
	v_mfma_f32_16x16x32_bf16 v[32:35], v[84:87], v[220:223], v[32:35]
	v_mfma_f32_16x16x32_bf16 v[32:35], v[96:99], v[224:227], v[32:35]
	v_mfma_f32_16x16x32_bf16 v[28:31], v[140:143], v[220:223], v[28:31]
	v_mfma_f32_16x16x32_bf16 v[28:31], v[144:147], v[224:227], v[28:31]
	v_mfma_f32_16x16x32_bf16 v[16:19], v[84:87], v[228:231], v[16:19]
	v_mfma_f32_16x16x32_bf16 v[16:19], v[96:99], v[232:235], v[16:19]
	v_mfma_f32_16x16x32_bf16 v[12:15], v[140:143], v[228:231], v[12:15]
	v_mfma_f32_16x16x32_bf16 v[12:15], v[144:147], v[232:235], v[12:15]
	s_setprio 0
	s_setprio 3
	v_mfma_f32_16x16x32_bf16 v[56:59], v[152:155], v[186:189], v[56:59]
	v_mfma_f32_16x16x32_bf16 v[56:59], v[156:159], v[208:211], v[56:59]
	v_mfma_f32_16x16x32_bf16 v[52:55], v[160:163], v[186:189], v[52:55]
	v_mfma_f32_16x16x32_bf16 v[52:55], v[182:185], v[208:211], v[52:55]
	v_mfma_f32_16x16x32_bf16 v[40:43], v[152:155], v[212:215], v[40:43]
	v_mfma_f32_16x16x32_bf16 v[40:43], v[156:159], v[216:219], v[40:43]
	v_mfma_f32_16x16x32_bf16 v[36:39], v[160:163], v[212:215], v[36:39]
	v_mfma_f32_16x16x32_bf16 v[36:39], v[182:185], v[216:219], v[36:39]
	v_mfma_f32_16x16x32_bf16 v[24:27], v[152:155], v[220:223], v[24:27]
	v_mfma_f32_16x16x32_bf16 v[24:27], v[156:159], v[224:227], v[24:27]
	v_mfma_f32_16x16x32_bf16 v[20:23], v[160:163], v[220:223], v[20:23]
	v_mfma_f32_16x16x32_bf16 v[20:23], v[182:185], v[224:227], v[20:23]
	v_mfma_f32_16x16x32_bf16 v[6:9], v[152:155], v[228:231], v[8:11]
	v_mfma_f32_16x16x32_bf16 v[8:11], v[156:159], v[232:235], v[6:9]
	v_mfma_f32_16x16x32_bf16 v[2:5], v[160:163], v[228:231], v[2:5]
	v_mfma_f32_16x16x32_bf16 v[4:7], v[182:185], v[232:235], v[2:5]
	s_setprio 0
	s_barrier
	s_add_i32 s95, s95, 2
	s_add_u32 s66, s66, 0x100
	s_addc_u32 s67, s67, 0
	s_cmp_gt_u32 s95, 61
	s_cbranch_scc1 .LBB0_237

; #define PG8_STAGE(bufoff, gbase, voff) do { _Pragma("unroll") for (int _i = 0; _i < 2; ++_i) \
;         __builtin_amdgcn_global_load_lds((const unsigned*)((const char*)(gbase) + (voff)[_i]), (LAS unsigned*)(lds + (bufoff) + ldsw + _i * 8192), 16, 0, 0); } while (0)
; #define PG8_LDA(dst, b, h) do { _Pragma("unroll") for (int m = 0; m < 4; ++m) _Pragma("unroll") for (int k = 0; k < 2; ++k) dst[m][k] = *(const LAS bf16x8*)(lds + PG8_SA(b, h) + aoff + m * 2048 + k * 1024); } while (0)
; #define PG8_LDB(dst, b, h) do { _Pragma("unroll") for (int n = 0; n < 2; ++n) _Pragma("unroll") for (int k = 0; k < 2; ++k) dst[n][k] = *(const LAS bf16x8*)(lds + PG8_SB(b, h) + boff + n * 2048 + k * 1024); } while (0)
; #define PG8_MMA(ai, bj, At, Bt) do { __builtin_amdgcn_s_setprio(3); _Pragma("unroll") for (int m = 0; m < 4; ++m) _Pragma("unroll") for (int n = 0; n < 2; ++n) _Pragma("unroll") for (int k = 0; k < 2; ++k) \
;         acc[ai][bj][m][n] = __builtin_amdgcn_mfma_f32_16x16x32_bf16(Bt[n][k], At[m][k], acc[ai][bj][m][n], 0, 0, 0); __builtin_amdgcn_s_setprio(0); } while (0)
; #define PG8_WAIT_V(n) asm volatile("s_waitcnt vmcnt(" #n ")" ::: "memory")
; #define PG8_WAIT_L(n) asm volatile("s_waitcnt lgkmcnt(" #n ")" ::: "memory")
; #define PG8_BAR __builtin_amdgcn_s_barrier()
; #define PG8_SCHED __builtin_amdgcn_sched_barrier(0)
; template <class Epi, class Sched, bool ALIGN_EPI = false, bool SP2 = false>
; __device__ __forceinline__ void gemm_phase(LAS unsigned char* lds, const Gemm g, const Sched& S, const Epi& E) {
;     ...
;             PG8_LDB(B0, 0, 0); PG8_LDB(B1, 0, 1); PG8_SCHED; PG8_LDA(At, 0, 0); PG8_STAGE(PG8_SA(1, 1), a1 + hsA, voffA);
;             PG8_WAIT_V(8); PG8_WAIT_L(0); PG8_BAR; PG8_MMA(0, 0, At, B0); PG8_MMA(0, 1, At, B1); PG8_BAR; PG8_SCHED;
;             PG8_LDA(At, 0, 1); PG8_STAGE(PG8_SB(0, 0), b2, voffB); PG8_STAGE(PG8_SB(0, 1), b2 + hsB, voffB); PG8_STAGE(PG8_SA(0, 0), a2, voffA);
;             PG8_WAIT_V(8); PG8_WAIT_L(0); PG8_BAR; PG8_MMA(1, 0, At, B0); PG8_MMA(1, 1, At, B1); PG8_BAR; PG8_SCHED;
.LBB0_309:
	ds_read_b128 v[112:115], v175
	ds_read_b128 v[132:135], v251
	ds_read_b128 v[136:139], v175 offset:2048
	ds_read_b128 v[140:143], v251 offset:2048
	ds_read_b128 v[144:147], v176
	ds_read_b128 v[148:151], v252
	ds_read_b128 v[184:187], v176 offset:2048
	ds_read_b128 v[188:191], v252 offset:2048
	s_add_u32 s24, s4, 0xffefc080
	s_addc_u32 s25, s5, -1
	s_cmp_eq_u32 s73, 60
	s_cselect_b32 s27, s11, s25
	s_cselect_b32 s26, s10, s24
	s_cselect_b32 s25, s21, s72
	s_cselect_b32 s24, s20, s71
	s_sub_u32 s100, s4, 0x104000
	s_subb_u32 s101, s5, 0
	v_lshl_add_u64 v[242:243], s[100:101], 0, v[152:153]
	s_mov_b32 m0, s42
	v_lshl_add_u64 v[244:245], s[100:101], 0, v[156:157]
	global_load_lds_dwordx4 v[242:243], off
	s_mov_b32 m0, s43
	s_nop 0
	global_load_lds_dwordx4 v[244:245], off
	v_lshl_add_u64 v[200:201], s[4:5], 0, v[164:165]
	s_add_i32 m0, s36, 0xc000
	ds_read_b128 v[192:195], v177
	ds_read_b128 v[196:199], v250
	ds_read_b128 v[206:209], v177 offset:2048
	ds_read_b128 v[210:213], v250 offset:2048
	ds_read_b128 v[214:217], v177 offset:4096
	ds_read_b128 v[218:221], v250 offset:4096
	ds_read_b128 v[222:225], v177 offset:6144
	ds_read_b128 v[226:229], v250 offset:6144
	global_load_lds_dwordx4 v[200:201], off
	v_lshl_add_u64 v[200:201], s[4:5], 0, v[166:167]
	s_add_i32 m0, s36, 0xe000
	s_nop 0
	global_load_lds_dwordx4 v[200:201], off
	s_waitcnt vmcnt(8)
	s_waitcnt lgkmcnt(0)
	s_barrier
	s_setprio 3
	s_waitcnt lgkmcnt(0)
	v_mfma_f32_16x16x32_bf16 v[128:131], v[112:115], v[192:195], v[128:131]
	v_mfma_f32_16x16x32_bf16 v[128:131], v[132:135], v[196:199], v[128:131]
	v_mfma_f32_16x16x32_bf16 v[124:127], v[136:139], v[192:195], v[124:127]
	v_mfma_f32_16x16x32_bf16 v[124:127], v[140:143], v[196:199], v[124:127]
	v_mfma_f32_16x16x32_bf16 v[108:111], v[112:115], v[206:209], v[108:111]
	v_mfma_f32_16x16x32_bf16 v[108:111], v[132:135], v[210:213], v[108:111]
	v_mfma_f32_16x16x32_bf16 v[104:107], v[136:139], v[206:209], v[104:107]
	v_mfma_f32_16x16x32_bf16 v[104:107], v[140:143], v[210:213], v[104:107]
	v_mfma_f32_16x16x32_bf16 v[92:95], v[112:115], v[214:217], v[92:95]
	v_mfma_f32_16x16x32_bf16 v[92:95], v[132:135], v[218:221], v[92:95]
	v_mfma_f32_16x16x32_bf16 v[88:91], v[136:139], v[214:217], v[88:91]
	v_mfma_f32_16x16x32_bf16 v[88:91], v[140:143], v[218:221], v[88:91]
	v_mfma_f32_16x16x32_bf16 v[76:79], v[112:115], v[222:225], v[76:79]
	v_mfma_f32_16x16x32_bf16 v[76:79], v[132:135], v[226:229], v[76:79]
	v_mfma_f32_16x16x32_bf16 v[72:75], v[136:139], v[222:225], v[72:75]
	v_mfma_f32_16x16x32_bf16 v[72:75], v[140:143], v[226:229], v[72:75]
	s_setprio 0
	s_setprio 3
	v_mfma_f32_16x16x32_bf16 v[120:123], v[144:147], v[192:195], v[120:123]
	v_mfma_f32_16x16x32_bf16 v[120:123], v[148:151], v[196:199], v[120:123]
	v_mfma_f32_16x16x32_bf16 v[116:119], v[184:187], v[192:195], v[116:119]
	v_mfma_f32_16x16x32_bf16 v[116:119], v[188:191], v[196:199], v[116:119]
	v_mfma_f32_16x16x32_bf16 v[100:103], v[144:147], v[206:209], v[100:103]
	v_mfma_f32_16x16x32_bf16 v[100:103], v[148:151], v[210:213], v[100:103]
	v_mfma_f32_16x16x32_bf16 v[96:99], v[184:187], v[206:209], v[96:99]
	v_mfma_f32_16x16x32_bf16 v[96:99], v[188:191], v[210:213], v[96:99]
	v_mfma_f32_16x16x32_bf16 v[84:87], v[144:147], v[214:217], v[84:87]
	v_mfma_f32_16x16x32_bf16 v[84:87], v[148:151], v[218:221], v[84:87]
	v_mfma_f32_16x16x32_bf16 v[80:83], v[184:187], v[214:217], v[80:83]
	v_mfma_f32_16x16x32_bf16 v[80:83], v[188:191], v[218:221], v[80:83]
	v_mfma_f32_16x16x32_bf16 v[68:71], v[144:147], v[222:225], v[68:71]
	v_mfma_f32_16x16x32_bf16 v[68:71], v[148:151], v[226:229], v[68:71]
	v_mfma_f32_16x16x32_bf16 v[64:67], v[184:187], v[222:225], v[64:67]
	v_mfma_f32_16x16x32_bf16 v[64:67], v[188:191], v[226:229], v[64:67]
	s_setprio 0
	s_barrier
	s_add_i32 s74, s45, s31
	v_lshl_add_u64 v[200:201], s[24:25], 0, v[154:155]
	s_mov_b32 m0, s74
	ds_read_b128 v[192:195], v177 offset:16384
	ds_read_b128 v[196:199], v250 offset:16384
	ds_read_b128 v[206:209], v177 offset:18432
	ds_read_b128 v[210:213], v250 offset:18432
	ds_read_b128 v[214:217], v177 offset:20480
	ds_read_b128 v[218:221], v250 offset:20480
	ds_read_b128 v[222:225], v177 offset:22528
	ds_read_b128 v[226:229], v250 offset:22528
	global_load_lds_dwordx4 v[200:201], off
	s_add_i32 m0, s74, 0x2000
	s_add_u32 s74, s24, 0x41000
	v_lshl_add_u64 v[230:231], s[24:25], 0, v[158:159]
	s_addc_u32 s75, s25, 0
	s_add_i32 s78, s46, s31
	global_load_lds_dwordx4 v[230:231], off
	v_lshl_add_u64 v[232:233], s[74:75], 0, v[154:155]
	s_mov_b32 m0, s78
	s_nop 0
	global_load_lds_dwordx4 v[232:233], off
	v_lshl_add_u64 v[232:233], s[74:75], 0, v[158:159]
	s_add_i32 m0, s78, 0x2000
	s_nop 0
	global_load_lds_dwordx4 v[232:233], off
	s_waitcnt vmcnt(6)
	s_waitcnt lgkmcnt(0)
	s_barrier
; #define PG8_STAGE(bufoff, gbase, voff) do { _Pragma("unroll") for (int _i = 0; _i < 2; ++_i) \
;         __builtin_amdgcn_global_load_lds((const unsigned*)((const char*)(gbase) + (voff)[_i]), (LAS unsigned*)(lds + (bufoff) + ldsw + _i * 8192), 16, 0, 0); } while (0)
; #define PG8_LDA(dst, b, h) do { _Pragma("unroll") for (int m = 0; m < 4; ++m) _Pragma("unroll") for (int k = 0; k < 2; ++k) dst[m][k] = *(const LAS bf16x8*)(lds + PG8_SA(b, h) + aoff + m * 2048 + k * 1024); } while (0)
; #define PG8_LDB(dst, b, h) do { _Pragma("unroll") for (int n = 0; n < 2; ++n) _Pragma("unroll") for (int k = 0; k < 2; ++k) dst[n][k] = *(const LAS bf16x8*)(lds + PG8_SB(b, h) + boff + n * 2048 + k * 1024); } while (0)
; #define PG8_MMA(ai, bj, At, Bt) do { __builtin_amdgcn_s_setprio(3); _Pragma("unroll") for (int m = 0; m < 4; ++m) _Pragma("unroll") for (int n = 0; n < 2; ++n) _Pragma("unroll") for (int k = 0; k < 2; ++k) \
;         acc[ai][bj][m][n] = __builtin_amdgcn_mfma_f32_16x16x32_bf16(Bt[n][k], At[m][k], acc[ai][bj][m][n], 0, 0, 0); __builtin_amdgcn_s_setprio(0); } while (0)
; #define PG8_WAIT_V(n) asm volatile("s_waitcnt vmcnt(" #n ")" ::: "memory")
; #define PG8_WAIT_L(n) asm volatile("s_waitcnt lgkmcnt(" #n ")" ::: "memory")
; #define PG8_BAR __builtin_amdgcn_s_barrier()
; #define PG8_SCHED __builtin_amdgcn_sched_barrier(0)
; template <class Epi, class Sched, bool ALIGN_EPI = false, bool SP2 = false>
; __device__ __forceinline__ void gemm_phase(LAS unsigned char* lds, const Gemm g, const Sched& S, const Epi& E) {
;     ...
;             PG8_WAIT_V(8); PG8_WAIT_L(0); PG8_BAR; PG8_MMA(1, 0, At, B0); PG8_MMA(1, 1, At, B1); PG8_BAR; PG8_SCHED;
;             PG8_LDB(B0, 1, 0); PG8_LDB(B1, 1, 1); PG8_SCHED; PG8_LDA(At, 1, 0); PG8_STAGE(PG8_SA(0, 1), a2 + hsA, voffA);
;             PG8_WAIT_V(8); PG8_WAIT_L(0); PG8_BAR; PG8_MMA(0, 0, At, B0); PG8_MMA(0, 1, At, B1); PG8_BAR; PG8_SCHED;
	s_setprio 3
	s_waitcnt lgkmcnt(0)
	v_mfma_f32_16x16x32_bf16 v[60:63], v[112:115], v[192:195], v[60:63]
	v_mfma_f32_16x16x32_bf16 v[60:63], v[132:135], v[196:199], v[60:63]
	v_mfma_f32_16x16x32_bf16 v[56:59], v[136:139], v[192:195], v[56:59]
	v_mfma_f32_16x16x32_bf16 v[56:59], v[140:143], v[196:199], v[56:59]
	v_mfma_f32_16x16x32_bf16 v[44:47], v[112:115], v[206:209], v[44:47]
	v_mfma_f32_16x16x32_bf16 v[44:47], v[132:135], v[210:213], v[44:47]
	v_mfma_f32_16x16x32_bf16 v[40:43], v[136:139], v[206:209], v[40:43]
	v_mfma_f32_16x16x32_bf16 v[40:43], v[140:143], v[210:213], v[40:43]
	v_mfma_f32_16x16x32_bf16 v[28:31], v[112:115], v[214:217], v[28:31]
	v_mfma_f32_16x16x32_bf16 v[28:31], v[132:135], v[218:221], v[28:31]
	v_mfma_f32_16x16x32_bf16 v[24:27], v[136:139], v[214:217], v[24:27]
	v_mfma_f32_16x16x32_bf16 v[24:27], v[140:143], v[218:221], v[24:27]
	v_mfma_f32_16x16x32_bf16 v[12:15], v[112:115], v[222:225], v[12:15]
	v_mfma_f32_16x16x32_bf16 v[12:15], v[132:135], v[226:229], v[12:15]
	v_mfma_f32_16x16x32_bf16 v[8:11], v[136:139], v[222:225], v[8:11]
	v_mfma_f32_16x16x32_bf16 v[8:11], v[140:143], v[226:229], v[8:11]
	s_setprio 0
	s_setprio 3
	v_mfma_f32_16x16x32_bf16 v[52:55], v[144:147], v[192:195], v[52:55]
	v_mfma_f32_16x16x32_bf16 v[52:55], v[148:151], v[196:199], v[52:55]
	v_mfma_f32_16x16x32_bf16 v[48:51], v[184:187], v[192:195], v[48:51]
	v_mfma_f32_16x16x32_bf16 v[48:51], v[188:191], v[196:199], v[48:51]
	v_mfma_f32_16x16x32_bf16 v[36:39], v[144:147], v[206:209], v[36:39]
	v_mfma_f32_16x16x32_bf16 v[36:39], v[148:151], v[210:213], v[36:39]
	v_mfma_f32_16x16x32_bf16 v[32:35], v[184:187], v[206:209], v[32:35]
	v_mfma_f32_16x16x32_bf16 v[32:35], v[188:191], v[210:213], v[32:35]
	v_mfma_f32_16x16x32_bf16 v[20:23], v[144:147], v[214:217], v[20:23]
	v_mfma_f32_16x16x32_bf16 v[20:23], v[148:151], v[218:221], v[20:23]
	v_mfma_f32_16x16x32_bf16 v[16:19], v[184:187], v[214:217], v[16:19]
	v_mfma_f32_16x16x32_bf16 v[16:19], v[188:191], v[218:221], v[16:19]
	v_mfma_f32_16x16x32_bf16 v[4:7], v[144:147], v[222:225], v[4:7]
	v_mfma_f32_16x16x32_bf16 v[4:7], v[148:151], v[226:229], v[4:7]
	v_mfma_f32_16x16x32_bf16 v[0:3], v[184:187], v[222:225], v[0:3]
	v_mfma_f32_16x16x32_bf16 v[0:3], v[188:191], v[226:229], v[0:3]
	s_setprio 0
	s_barrier
	s_add_i32 s74, 0, 0x18000
	s_add_i32 s75, 0, 0x1c000
	v_add_u32_e32 v140, s74, v173
	v_xor_b32_e32 v253, 64, v140
	v_add_u32_e32 v188, s75, v173
	v_xor_b32_e32 v254, 64, v188
	ds_read_b128 v[112:115], v140
	ds_read_b128 v[132:135], v253
	ds_read_b128 v[136:139], v140 offset:2048
	ds_read_b128 v[140:143], v253 offset:2048
	ds_read_b128 v[144:147], v188
	ds_read_b128 v[148:151], v254
	ds_read_b128 v[184:187], v188 offset:2048
	ds_read_b128 v[188:191], v254 offset:2048
	v_lshl_add_u64 v[242:243], s[26:27], 0, v[152:153]
	s_mov_b32 m0, s36
	v_lshl_add_u64 v[244:245], s[26:27], 0, v[156:157]
	global_load_lds_dwordx4 v[242:243], off
	s_mov_b32 m0, s37
	s_nop 0
	global_load_lds_dwordx4 v[244:245], off
	s_add_u32 s26, s26, 0x104000
	s_addc_u32 s27, s27, 0
	s_mov_b32 m0, s38
	v_lshl_add_u64 v[236:237], s[26:27], 0, v[152:153]
	ds_read_b128 v[192:195], v177 offset:32768
	ds_read_b128 v[196:199], v250 offset:32768
	ds_read_b128 v[206:209], v177 offset:34816
	ds_read_b128 v[210:213], v250 offset:34816
	ds_read_b128 v[214:217], v177 offset:36864
	ds_read_b128 v[218:221], v250 offset:36864
	ds_read_b128 v[222:225], v177 offset:38912
	ds_read_b128 v[226:229], v250 offset:38912
	global_load_lds_dwordx4 v[236:237], off
	v_lshl_add_u64 v[236:237], s[26:27], 0, v[156:157]
	s_mov_b32 m0, s39
	s_nop 0
	global_load_lds_dwordx4 v[236:237], off
	s_waitcnt vmcnt(8)
	s_waitcnt lgkmcnt(0)
	s_barrier
; #define PG8_STAGE(bufoff, gbase, voff) do { _Pragma("unroll") for (int _i = 0; _i < 2; ++_i) \
;         __builtin_amdgcn_global_load_lds((const unsigned*)((const char*)(gbase) + (voff)[_i]), (LAS unsigned*)(lds + (bufoff) + ldsw + _i * 8192), 16, 0, 0); } while (0)
; #define PG8_LDA(dst, b, h) do { _Pragma("unroll") for (int m = 0; m < 4; ++m) _Pragma("unroll") for (int k = 0; k < 2; ++k) dst[m][k] = *(const LAS bf16x8*)(lds + PG8_SA(b, h) + aoff + m * 2048 + k * 1024); } while (0)
; #define PG8_MMA(ai, bj, At, Bt) do { __builtin_amdgcn_s_setprio(3); _Pragma("unroll") for (int m = 0; m < 4; ++m) _Pragma("unroll") for (int n = 0; n < 2; ++n) _Pragma("unroll") for (int k = 0; k < 2; ++k) \
;         acc[ai][bj][m][n] = __builtin_amdgcn_mfma_f32_16x16x32_bf16(Bt[n][k], At[m][k], acc[ai][bj][m][n], 0, 0, 0); __builtin_amdgcn_s_setprio(0); } while (0)
; #define PG8_WAIT_V(n) asm volatile("s_waitcnt vmcnt(" #n ")" ::: "memory")
; #define PG8_WAIT_L(n) asm volatile("s_waitcnt lgkmcnt(" #n ")" ::: "memory")
; #define PG8_BAR __builtin_amdgcn_s_barrier()
; #define PG8_SCHED __builtin_amdgcn_sched_barrier(0)
; template <class Epi, class Sched, bool ALIGN_EPI = false, bool SP2 = false>
; __device__ __forceinline__ void gemm_phase(LAS unsigned char* lds, const Gemm g, const Sched& S, const Epi& E) {
;     ...
;             PG8_WAIT_V(8); PG8_WAIT_L(0); PG8_BAR; PG8_MMA(0, 0, At, B0); PG8_MMA(0, 1, At, B1); PG8_BAR; PG8_SCHED;
;             PG8_LDA(At, 1, 1); PG8_STAGE(PG8_SB(1, 0), b3, voffB); PG8_STAGE(PG8_SB(1, 1), b3 + hsB, voffB); PG8_STAGE(PG8_SA(1, 0), a3, voffA);
;             PG8_WAIT_V(8); PG8_WAIT_L(0); PG8_BAR; PG8_MMA(1, 0, At, B0); PG8_MMA(1, 1, At, B1); PG8_BAR; PG8_SCHED;
	s_setprio 3
	s_waitcnt lgkmcnt(0)
	v_mfma_f32_16x16x32_bf16 v[128:131], v[112:115], v[192:195], v[128:131]
	v_mfma_f32_16x16x32_bf16 v[128:131], v[132:135], v[196:199], v[128:131]
	v_mfma_f32_16x16x32_bf16 v[124:127], v[136:139], v[192:195], v[124:127]
	v_mfma_f32_16x16x32_bf16 v[124:127], v[140:143], v[196:199], v[124:127]
	v_mfma_f32_16x16x32_bf16 v[108:111], v[112:115], v[206:209], v[108:111]
	v_mfma_f32_16x16x32_bf16 v[108:111], v[132:135], v[210:213], v[108:111]
	v_mfma_f32_16x16x32_bf16 v[104:107], v[136:139], v[206:209], v[104:107]
	v_mfma_f32_16x16x32_bf16 v[104:107], v[140:143], v[210:213], v[104:107]
	v_mfma_f32_16x16x32_bf16 v[92:95], v[112:115], v[214:217], v[92:95]
	v_mfma_f32_16x16x32_bf16 v[92:95], v[132:135], v[218:221], v[92:95]
	v_mfma_f32_16x16x32_bf16 v[88:91], v[136:139], v[214:217], v[88:91]
	v_mfma_f32_16x16x32_bf16 v[88:91], v[140:143], v[218:221], v[88:91]
	v_mfma_f32_16x16x32_bf16 v[76:79], v[112:115], v[222:225], v[76:79]
	v_mfma_f32_16x16x32_bf16 v[76:79], v[132:135], v[226:229], v[76:79]
	v_mfma_f32_16x16x32_bf16 v[72:75], v[136:139], v[222:225], v[72:75]
	v_mfma_f32_16x16x32_bf16 v[72:75], v[140:143], v[226:229], v[72:75]
	s_setprio 0
	s_setprio 3
	v_mfma_f32_16x16x32_bf16 v[120:123], v[144:147], v[192:195], v[120:123]
	v_mfma_f32_16x16x32_bf16 v[120:123], v[148:151], v[196:199], v[120:123]
	v_mfma_f32_16x16x32_bf16 v[116:119], v[184:187], v[192:195], v[116:119]
	v_mfma_f32_16x16x32_bf16 v[116:119], v[188:191], v[196:199], v[116:119]
	v_mfma_f32_16x16x32_bf16 v[100:103], v[144:147], v[206:209], v[100:103]
	v_mfma_f32_16x16x32_bf16 v[100:103], v[148:151], v[210:213], v[100:103]
	v_mfma_f32_16x16x32_bf16 v[96:99], v[184:187], v[206:209], v[96:99]
	v_mfma_f32_16x16x32_bf16 v[96:99], v[188:191], v[210:213], v[96:99]
	v_mfma_f32_16x16x32_bf16 v[84:87], v[144:147], v[214:217], v[84:87]
	v_mfma_f32_16x16x32_bf16 v[84:87], v[148:151], v[218:221], v[84:87]
	v_mfma_f32_16x16x32_bf16 v[80:83], v[184:187], v[214:217], v[80:83]
	v_mfma_f32_16x16x32_bf16 v[80:83], v[188:191], v[218:221], v[80:83]
	v_mfma_f32_16x16x32_bf16 v[68:71], v[144:147], v[222:225], v[68:71]
	v_mfma_f32_16x16x32_bf16 v[68:71], v[148:151], v[226:229], v[68:71]
	v_mfma_f32_16x16x32_bf16 v[64:67], v[184:187], v[222:225], v[64:67]
	v_mfma_f32_16x16x32_bf16 v[64:67], v[188:191], v[226:229], v[64:67]
	s_setprio 0
	s_barrier
	s_add_i32 s26, s74, s31
	v_lshl_add_u64 v[200:201], v[200:201], 0, s[14:15]
	s_mov_b32 m0, s26
	ds_read_b128 v[192:195], v177 offset:49152
	ds_read_b128 v[196:199], v250 offset:49152
	ds_read_b128 v[206:209], v177 offset:51200
	ds_read_b128 v[210:213], v250 offset:51200
	ds_read_b128 v[214:217], v177 offset:53248
	ds_read_b128 v[218:221], v250 offset:53248
	ds_read_b128 v[222:225], v177 offset:55296
	ds_read_b128 v[226:229], v250 offset:55296
	global_load_lds_dwordx4 v[200:201], off
	s_add_i32 m0, s26, 0x2000
	s_add_u32 s24, s24, 0x41080
	v_lshl_add_u64 v[200:201], v[230:231], 0, s[14:15]
	s_addc_u32 s25, s25, 0
	s_add_i32 s26, s75, s31
	global_load_lds_dwordx4 v[200:201], off
	v_lshl_add_u64 v[200:201], s[24:25], 0, v[154:155]
	s_mov_b32 m0, s26
	s_nop 0
	global_load_lds_dwordx4 v[200:201], off
	v_lshl_add_u64 v[200:201], s[24:25], 0, v[158:159]
	s_add_i32 m0, s26, 0x2000
	s_nop 0
	global_load_lds_dwordx4 v[200:201], off
	s_waitcnt vmcnt(6)
	s_waitcnt lgkmcnt(0)
	s_barrier
	s_setprio 3
	s_waitcnt lgkmcnt(0)
	v_mfma_f32_16x16x32_bf16 v[60:63], v[112:115], v[192:195], v[60:63]
	v_mfma_f32_16x16x32_bf16 v[60:63], v[132:135], v[196:199], v[60:63]
	v_mfma_f32_16x16x32_bf16 v[56:59], v[136:139], v[192:195], v[56:59]
	v_mfma_f32_16x16x32_bf16 v[56:59], v[140:143], v[196:199], v[56:59]
	v_mfma_f32_16x16x32_bf16 v[44:47], v[112:115], v[206:209], v[44:47]
	v_mfma_f32_16x16x32_bf16 v[44:47], v[132:135], v[210:213], v[44:47]
	v_mfma_f32_16x16x32_bf16 v[40:43], v[136:139], v[206:209], v[40:43]
	v_mfma_f32_16x16x32_bf16 v[40:43], v[140:143], v[210:213], v[40:43]
	v_mfma_f32_16x16x32_bf16 v[28:31], v[112:115], v[214:217], v[28:31]
	v_mfma_f32_16x16x32_bf16 v[28:31], v[132:135], v[218:221], v[28:31]
	v_mfma_f32_16x16x32_bf16 v[24:27], v[136:139], v[214:217], v[24:27]
	v_mfma_f32_16x16x32_bf16 v[24:27], v[140:143], v[218:221], v[24:27]
	v_mfma_f32_16x16x32_bf16 v[12:15], v[112:115], v[222:225], v[12:15]
	v_mfma_f32_16x16x32_bf16 v[12:15], v[132:135], v[226:229], v[12:15]
	v_mfma_f32_16x16x32_bf16 v[8:11], v[136:139], v[222:225], v[8:11]
	v_mfma_f32_16x16x32_bf16 v[8:11], v[140:143], v[226:229], v[8:11]
	s_setprio 0
	s_setprio 3
	v_mfma_f32_16x16x32_bf16 v[52:55], v[144:147], v[192:195], v[52:55]
	v_mfma_f32_16x16x32_bf16 v[52:55], v[148:151], v[196:199], v[52:55]
	v_mfma_f32_16x16x32_bf16 v[48:51], v[184:187], v[192:195], v[48:51]
	v_mfma_f32_16x16x32_bf16 v[48:51], v[188:191], v[196:199], v[48:51]
	v_mfma_f32_16x16x32_bf16 v[36:39], v[144:147], v[206:209], v[36:39]
	v_mfma_f32_16x16x32_bf16 v[36:39], v[148:151], v[210:213], v[36:39]
	v_mfma_f32_16x16x32_bf16 v[32:35], v[184:187], v[206:209], v[32:35]
	v_mfma_f32_16x16x32_bf16 v[32:35], v[188:191], v[210:213], v[32:35]
	v_mfma_f32_16x16x32_bf16 v[20:23], v[144:147], v[214:217], v[20:23]
	v_mfma_f32_16x16x32_bf16 v[20:23], v[148:151], v[218:221], v[20:23]
	v_mfma_f32_16x16x32_bf16 v[16:19], v[184:187], v[214:217], v[16:19]
	v_mfma_f32_16x16x32_bf16 v[16:19], v[188:191], v[218:221], v[16:19]
	v_mfma_f32_16x16x32_bf16 v[4:7], v[144:147], v[222:225], v[4:7]
	v_mfma_f32_16x16x32_bf16 v[4:7], v[148:151], v[226:229], v[4:7]
	v_mfma_f32_16x16x32_bf16 v[0:3], v[184:187], v[222:225], v[0:3]
	v_mfma_f32_16x16x32_bf16 v[0:3], v[188:191], v[226:229], v[0:3]
	s_setprio 0
	s_barrier
	s_add_i32 s73, s73, 2
	s_add_u32 s4, s4, 0x100
	s_addc_u32 s5, s5, 0
	s_add_u32 s71, s71, 0x100
	s_addc_u32 s72, s72, 0
	s_cmp_gt_u32 s73, 61
	s_cbranch_scc0 .LBB0_309
	s_and_b64 vcc, exec, s[16:17]
	s_cbranch_vccz .LBB0_312
	s_barrier

; #define PG8_STAGE(bufoff, gbase, voff) do { _Pragma("unroll") for (int _i = 0; _i < 2; ++_i) \
;         __builtin_amdgcn_global_load_lds((const unsigned*)((const char*)(gbase) + (voff)[_i]), (LAS unsigned*)(lds + (bufoff) + ldsw + _i * 8192), 16, 0, 0); } while (0)
; #define PG8_LDA(dst, b, h) do { _Pragma("unroll") for (int m = 0; m < 4; ++m) _Pragma("unroll") for (int k = 0; k < 2; ++k) dst[m][k] = *(const LAS bf16x8*)(lds + PG8_SA(b, h) + aoff + m * 2048 + k * 1024); } while (0)
; #define PG8_LDB(dst, b, h) do { _Pragma("unroll") for (int n = 0; n < 2; ++n) _Pragma("unroll") for (int k = 0; k < 2; ++k) dst[n][k] = *(const LAS bf16x8*)(lds + PG8_SB(b, h) + boff + n * 2048 + k * 1024); } while (0)
; #define PG8_MMA(ai, bj, At, Bt) do { __builtin_amdgcn_s_setprio(3); _Pragma("unroll") for (int m = 0; m < 4; ++m) _Pragma("unroll") for (int n = 0; n < 2; ++n) _Pragma("unroll") for (int k = 0; k < 2; ++k) \
;         acc[ai][bj][m][n] = __builtin_amdgcn_mfma_f32_16x16x32_bf16(Bt[n][k], At[m][k], acc[ai][bj][m][n], 0, 0, 0); __builtin_amdgcn_s_setprio(0); } while (0)
; #define PG8_WAIT_V(n) asm volatile("s_waitcnt vmcnt(" #n ")" ::: "memory")
; #define PG8_WAIT_L(n) asm volatile("s_waitcnt lgkmcnt(" #n ")" ::: "memory")
; #define PG8_BAR __builtin_amdgcn_s_barrier()
; #define PG8_SCHED __builtin_amdgcn_sched_barrier(0)
; template <class Epi, class Sched, bool ALIGN_EPI = false, bool SP2 = false>
; __device__ __forceinline__ void gemm_phase(LAS unsigned char* lds, const Gemm g, const Sched& S, const Epi& E) {
;     ...
;             PG8_LDB(B0, 0, 0); PG8_LDB(B1, 0, 1); PG8_SCHED; PG8_LDA(At, 0, 0); PG8_STAGE(PG8_SA(1, 1), a1 + hsA, voffA);
;             PG8_WAIT_V(8); PG8_WAIT_L(0); PG8_BAR; PG8_MMA(0, 0, At, B0); PG8_MMA(0, 1, At, B1); PG8_BAR; PG8_SCHED;
;             PG8_LDA(At, 0, 1); PG8_STAGE(PG8_SB(0, 0), b2, voffB); PG8_STAGE(PG8_SB(0, 1), b2 + hsB, voffB); PG8_STAGE(PG8_SA(0, 0), a2, voffA);
;             PG8_WAIT_V(8); PG8_WAIT_L(0); PG8_BAR; PG8_MMA(1, 0, At, B0); PG8_MMA(1, 1, At, B1); PG8_BAR; PG8_SCHED;
.LBB0_350:
	ds_read_b128 v[140:143], v149
	ds_read_b128 v[156:159], v251
	ds_read_b128 v[160:163], v149 offset:2048
	ds_read_b128 v[164:167], v251 offset:2048
	ds_read_b128 v[168:171], v150
	ds_read_b128 v[172:175], v252
	ds_read_b128 v[176:179], v150 offset:2048
	ds_read_b128 v[180:183], v252 offset:2048
	s_add_u32 s16, s14, 0xffbfc080
	s_addc_u32 s17, s15, -1
	s_cmpk_eq_i32 s50, 0xfc
	s_cselect_b32 s21, s5, s17
	s_cselect_b32 s20, s4, s16
	s_cselect_b32 s17, s13, s49
	s_cselect_b32 s16, s12, s48
	s_sub_u32 s100, s14, 0x404000
	s_subb_u32 s101, s15, 0
	v_lshl_add_u64 v[242:243], s[100:101], 0, v[128:129]
	s_mov_b32 m0, s33
	v_lshl_add_u64 v[244:245], s[100:101], 0, v[130:131]
	global_load_lds_dwordx4 v[242:243], off
	s_mov_b32 m0, s38
	s_nop 0
	global_load_lds_dwordx4 v[244:245], off
	v_lshl_add_u64 v[144:145], s[14:15], 0, v[132:133]
	s_add_i32 m0, s26, 0xc000
	ds_read_b128 v[184:187], v151
	ds_read_b128 v[188:191], v250
	ds_read_b128 v[192:195], v151 offset:2048
	ds_read_b128 v[196:199], v250 offset:2048
	ds_read_b128 v[200:203], v151 offset:4096
	ds_read_b128 v[204:207], v250 offset:4096
	ds_read_b128 v[208:211], v151 offset:6144
	ds_read_b128 v[212:215], v250 offset:6144
	global_load_lds_dwordx4 v[144:145], off
	v_lshl_add_u64 v[144:145], s[14:15], 0, v[134:135]
	s_add_i32 m0, s26, 0xe000
	s_nop 0
	global_load_lds_dwordx4 v[144:145], off
	s_waitcnt vmcnt(8)
	s_waitcnt lgkmcnt(0)
	s_barrier
	s_setprio 3
	s_waitcnt lgkmcnt(0)
	v_mfma_f32_16x16x32_bf16 v[124:127], v[140:143], v[184:187], v[124:127]
	v_mfma_f32_16x16x32_bf16 v[124:127], v[156:159], v[188:191], v[124:127]
	v_mfma_f32_16x16x32_bf16 v[120:123], v[160:163], v[184:187], v[120:123]
	v_mfma_f32_16x16x32_bf16 v[120:123], v[164:167], v[188:191], v[120:123]
	v_mfma_f32_16x16x32_bf16 v[108:111], v[140:143], v[192:195], v[108:111]
	v_mfma_f32_16x16x32_bf16 v[108:111], v[156:159], v[196:199], v[108:111]
	v_mfma_f32_16x16x32_bf16 v[104:107], v[160:163], v[192:195], v[104:107]
	v_mfma_f32_16x16x32_bf16 v[104:107], v[164:167], v[196:199], v[104:107]
	v_mfma_f32_16x16x32_bf16 v[92:95], v[140:143], v[200:203], v[92:95]
	v_mfma_f32_16x16x32_bf16 v[92:95], v[156:159], v[204:207], v[92:95]
	v_mfma_f32_16x16x32_bf16 v[88:91], v[160:163], v[200:203], v[88:91]
	v_mfma_f32_16x16x32_bf16 v[88:91], v[164:167], v[204:207], v[88:91]
	v_mfma_f32_16x16x32_bf16 v[76:79], v[140:143], v[208:211], v[76:79]
	v_mfma_f32_16x16x32_bf16 v[76:79], v[156:159], v[212:215], v[76:79]
	v_mfma_f32_16x16x32_bf16 v[72:75], v[160:163], v[208:211], v[72:75]
	v_mfma_f32_16x16x32_bf16 v[72:75], v[164:167], v[212:215], v[72:75]
	s_setprio 0
	s_setprio 3
	v_mfma_f32_16x16x32_bf16 v[116:119], v[168:171], v[184:187], v[116:119]
	v_mfma_f32_16x16x32_bf16 v[116:119], v[172:175], v[188:191], v[116:119]
	v_mfma_f32_16x16x32_bf16 v[112:115], v[176:179], v[184:187], v[112:115]
	v_mfma_f32_16x16x32_bf16 v[112:115], v[180:183], v[188:191], v[112:115]
	v_mfma_f32_16x16x32_bf16 v[100:103], v[168:171], v[192:195], v[100:103]
	v_mfma_f32_16x16x32_bf16 v[100:103], v[172:175], v[196:199], v[100:103]
	v_mfma_f32_16x16x32_bf16 v[96:99], v[176:179], v[192:195], v[96:99]
	v_mfma_f32_16x16x32_bf16 v[96:99], v[180:183], v[196:199], v[96:99]
	v_mfma_f32_16x16x32_bf16 v[84:87], v[168:171], v[200:203], v[84:87]
	v_mfma_f32_16x16x32_bf16 v[84:87], v[172:175], v[204:207], v[84:87]
	v_mfma_f32_16x16x32_bf16 v[80:83], v[176:179], v[200:203], v[80:83]
	v_mfma_f32_16x16x32_bf16 v[80:83], v[180:183], v[204:207], v[80:83]
	v_mfma_f32_16x16x32_bf16 v[68:71], v[168:171], v[208:211], v[68:71]
	v_mfma_f32_16x16x32_bf16 v[68:71], v[172:175], v[212:215], v[68:71]
	v_mfma_f32_16x16x32_bf16 v[64:67], v[176:179], v[208:211], v[64:67]
	v_mfma_f32_16x16x32_bf16 v[64:67], v[180:183], v[212:215], v[64:67]
	s_setprio 0
	s_barrier
	s_add_i32 s51, s41, s25
	v_lshl_add_u64 v[144:145], s[16:17], 0, v[128:129]
	s_mov_b32 m0, s51
	ds_read_b128 v[184:187], v151 offset:16384
	ds_read_b128 v[188:191], v250 offset:16384
	ds_read_b128 v[192:195], v151 offset:18432
	ds_read_b128 v[196:199], v250 offset:18432
	ds_read_b128 v[200:203], v151 offset:20480
	ds_read_b128 v[204:207], v250 offset:20480
	ds_read_b128 v[208:211], v151 offset:22528
	ds_read_b128 v[212:215], v250 offset:22528
	global_load_lds_dwordx4 v[144:145], off
	s_add_i32 m0, s51, 0x2000
	s_add_u32 s52, s16, 0x404000
	v_lshl_add_u64 v[216:217], s[16:17], 0, v[130:131]
	s_addc_u32 s53, s17, 0
	s_add_i32 s51, s42, s25
	global_load_lds_dwordx4 v[216:217], off
	v_lshl_add_u64 v[218:219], s[52:53], 0, v[128:129]
	s_mov_b32 m0, s51
	s_nop 0
	global_load_lds_dwordx4 v[218:219], off
	v_lshl_add_u64 v[218:219], s[52:53], 0, v[130:131]
	s_add_i32 m0, s51, 0x2000
	s_nop 0
	global_load_lds_dwordx4 v[218:219], off
	s_waitcnt vmcnt(6)
	s_waitcnt lgkmcnt(0)
	s_barrier
; #define PG8_STAGE(bufoff, gbase, voff) do { _Pragma("unroll") for (int _i = 0; _i < 2; ++_i) \
;         __builtin_amdgcn_global_load_lds((const unsigned*)((const char*)(gbase) + (voff)[_i]), (LAS unsigned*)(lds + (bufoff) + ldsw + _i * 8192), 16, 0, 0); } while (0)
; #define PG8_LDA(dst, b, h) do { _Pragma("unroll") for (int m = 0; m < 4; ++m) _Pragma("unroll") for (int k = 0; k < 2; ++k) dst[m][k] = *(const LAS bf16x8*)(lds + PG8_SA(b, h) + aoff + m * 2048 + k * 1024); } while (0)
; #define PG8_LDB(dst, b, h) do { _Pragma("unroll") for (int n = 0; n < 2; ++n) _Pragma("unroll") for (int k = 0; k < 2; ++k) dst[n][k] = *(const LAS bf16x8*)(lds + PG8_SB(b, h) + boff + n * 2048 + k * 1024); } while (0)
; #define PG8_MMA(ai, bj, At, Bt) do { __builtin_amdgcn_s_setprio(3); _Pragma("unroll") for (int m = 0; m < 4; ++m) _Pragma("unroll") for (int n = 0; n < 2; ++n) _Pragma("unroll") for (int k = 0; k < 2; ++k) \
;         acc[ai][bj][m][n] = __builtin_amdgcn_mfma_f32_16x16x32_bf16(Bt[n][k], At[m][k], acc[ai][bj][m][n], 0, 0, 0); __builtin_amdgcn_s_setprio(0); } while (0)
; #define PG8_WAIT_V(n) asm volatile("s_waitcnt vmcnt(" #n ")" ::: "memory")
; #define PG8_WAIT_L(n) asm volatile("s_waitcnt lgkmcnt(" #n ")" ::: "memory")
; #define PG8_BAR __builtin_amdgcn_s_barrier()
; #define PG8_SCHED __builtin_amdgcn_sched_barrier(0)
; template <class Epi, class Sched, bool ALIGN_EPI = false, bool SP2 = false>
; __device__ __forceinline__ void gemm_phase(LAS unsigned char* lds, const Gemm g, const Sched& S, const Epi& E) {
;     ...
;             PG8_WAIT_V(8); PG8_WAIT_L(0); PG8_BAR; PG8_MMA(1, 0, At, B0); PG8_MMA(1, 1, At, B1); PG8_BAR; PG8_SCHED;
;             PG8_LDB(B0, 1, 0); PG8_LDB(B1, 1, 1); PG8_SCHED; PG8_LDA(At, 1, 0); PG8_STAGE(PG8_SA(0, 1), a2 + hsA, voffA);
;             PG8_WAIT_V(8); PG8_WAIT_L(0); PG8_BAR; PG8_MMA(0, 0, At, B0); PG8_MMA(0, 1, At, B1); PG8_BAR; PG8_SCHED;
	s_setprio 3
	s_waitcnt lgkmcnt(0)
	v_mfma_f32_16x16x32_bf16 v[60:63], v[140:143], v[184:187], v[60:63]
	v_mfma_f32_16x16x32_bf16 v[60:63], v[156:159], v[188:191], v[60:63]
	v_mfma_f32_16x16x32_bf16 v[56:59], v[160:163], v[184:187], v[56:59]
	v_mfma_f32_16x16x32_bf16 v[56:59], v[164:167], v[188:191], v[56:59]
	v_mfma_f32_16x16x32_bf16 v[44:47], v[140:143], v[192:195], v[44:47]
	v_mfma_f32_16x16x32_bf16 v[44:47], v[156:159], v[196:199], v[44:47]
	v_mfma_f32_16x16x32_bf16 v[40:43], v[160:163], v[192:195], v[40:43]
	v_mfma_f32_16x16x32_bf16 v[40:43], v[164:167], v[196:199], v[40:43]
	v_mfma_f32_16x16x32_bf16 v[28:31], v[140:143], v[200:203], v[28:31]
	v_mfma_f32_16x16x32_bf16 v[28:31], v[156:159], v[204:207], v[28:31]
	v_mfma_f32_16x16x32_bf16 v[24:27], v[160:163], v[200:203], v[24:27]
	v_mfma_f32_16x16x32_bf16 v[24:27], v[164:167], v[204:207], v[24:27]
	v_mfma_f32_16x16x32_bf16 v[12:15], v[140:143], v[208:211], v[12:15]
	v_mfma_f32_16x16x32_bf16 v[12:15], v[156:159], v[212:215], v[12:15]
	v_mfma_f32_16x16x32_bf16 v[8:11], v[160:163], v[208:211], v[8:11]
	v_mfma_f32_16x16x32_bf16 v[8:11], v[164:167], v[212:215], v[8:11]
	s_setprio 0
	s_setprio 3
	v_mfma_f32_16x16x32_bf16 v[52:55], v[168:171], v[184:187], v[52:55]
	v_mfma_f32_16x16x32_bf16 v[52:55], v[172:175], v[188:191], v[52:55]
	v_mfma_f32_16x16x32_bf16 v[48:51], v[176:179], v[184:187], v[48:51]
	v_mfma_f32_16x16x32_bf16 v[48:51], v[180:183], v[188:191], v[48:51]
	v_mfma_f32_16x16x32_bf16 v[36:39], v[168:171], v[192:195], v[36:39]
	v_mfma_f32_16x16x32_bf16 v[36:39], v[172:175], v[196:199], v[36:39]
	v_mfma_f32_16x16x32_bf16 v[32:35], v[176:179], v[192:195], v[32:35]
	v_mfma_f32_16x16x32_bf16 v[32:35], v[180:183], v[196:199], v[32:35]
	v_mfma_f32_16x16x32_bf16 v[20:23], v[168:171], v[200:203], v[20:23]
	v_mfma_f32_16x16x32_bf16 v[20:23], v[172:175], v[204:207], v[20:23]
	v_mfma_f32_16x16x32_bf16 v[16:19], v[176:179], v[200:203], v[16:19]
	v_mfma_f32_16x16x32_bf16 v[16:19], v[180:183], v[204:207], v[16:19]
	v_mfma_f32_16x16x32_bf16 v[4:7], v[168:171], v[208:211], v[4:7]
	v_mfma_f32_16x16x32_bf16 v[4:7], v[172:175], v[212:215], v[4:7]
	v_mfma_f32_16x16x32_bf16 v[0:3], v[176:179], v[208:211], v[0:3]
	v_mfma_f32_16x16x32_bf16 v[0:3], v[180:183], v[212:215], v[0:3]
	s_setprio 0
	s_barrier
	s_add_i32 s51, 0, 0x18000
	v_add_u32_e32 v155, s51, v146
	v_xor_b32_e32 v253, 64, v155
	s_add_i32 s52, 0, 0x1c000
	ds_read_b128 v[140:143], v155
	ds_read_b128 v[156:159], v253
	ds_read_b128 v[160:163], v155 offset:2048
	ds_read_b128 v[164:167], v253 offset:2048
	v_add_u32_e32 v155, s52, v146
	v_xor_b32_e32 v253, 64, v155
	ds_read_b128 v[168:171], v155
	ds_read_b128 v[172:175], v253
	ds_read_b128 v[176:179], v155 offset:2048
	ds_read_b128 v[180:183], v253 offset:2048
	v_lshl_add_u64 v[242:243], s[20:21], 0, v[128:129]
	s_mov_b32 m0, s26
	v_lshl_add_u64 v[244:245], s[20:21], 0, v[130:131]
	global_load_lds_dwordx4 v[242:243], off
	s_mov_b32 m0, s27
	s_nop 0
	global_load_lds_dwordx4 v[244:245], off
	s_add_u32 s20, s20, 0x404000
	s_addc_u32 s21, s21, 0
	s_mov_b32 m0, s30
	v_lshl_add_u64 v[222:223], s[20:21], 0, v[128:129]
	ds_read_b128 v[184:187], v151 offset:32768
	ds_read_b128 v[188:191], v250 offset:32768
	ds_read_b128 v[192:195], v151 offset:34816
	ds_read_b128 v[196:199], v250 offset:34816
	ds_read_b128 v[200:203], v151 offset:36864
	ds_read_b128 v[204:207], v250 offset:36864
	ds_read_b128 v[208:211], v151 offset:38912
	ds_read_b128 v[212:215], v250 offset:38912
	global_load_lds_dwordx4 v[222:223], off
	v_lshl_add_u64 v[222:223], s[20:21], 0, v[130:131]
	s_mov_b32 m0, s31
	s_nop 0
	global_load_lds_dwordx4 v[222:223], off
	s_waitcnt vmcnt(8)
	s_waitcnt lgkmcnt(0)
	s_barrier
; #define PG8_STAGE(bufoff, gbase, voff) do { _Pragma("unroll") for (int _i = 0; _i < 2; ++_i) \
;         __builtin_amdgcn_global_load_lds((const unsigned*)((const char*)(gbase) + (voff)[_i]), (LAS unsigned*)(lds + (bufoff) + ldsw + _i * 8192), 16, 0, 0); } while (0)
; #define PG8_LDA(dst, b, h) do { _Pragma("unroll") for (int m = 0; m < 4; ++m) _Pragma("unroll") for (int k = 0; k < 2; ++k) dst[m][k] = *(const LAS bf16x8*)(lds + PG8_SA(b, h) + aoff + m * 2048 + k * 1024); } while (0)
; #define PG8_MMA(ai, bj, At, Bt) do { __builtin_amdgcn_s_setprio(3); _Pragma("unroll") for (int m = 0; m < 4; ++m) _Pragma("unroll") for (int n = 0; n < 2; ++n) _Pragma("unroll") for (int k = 0; k < 2; ++k) \
;         acc[ai][bj][m][n] = __builtin_amdgcn_mfma_f32_16x16x32_bf16(Bt[n][k], At[m][k], acc[ai][bj][m][n], 0, 0, 0); __builtin_amdgcn_s_setprio(0); } while (0)
; #define PG8_WAIT_V(n) asm volatile("s_waitcnt vmcnt(" #n ")" ::: "memory")
; #define PG8_WAIT_L(n) asm volatile("s_waitcnt lgkmcnt(" #n ")" ::: "memory")
; #define PG8_BAR __builtin_amdgcn_s_barrier()
; #define PG8_SCHED __builtin_amdgcn_sched_barrier(0)
; template <class Epi, class Sched, bool ALIGN_EPI = false, bool SP2 = false>
; __device__ __forceinline__ void gemm_phase(LAS unsigned char* lds, const Gemm g, const Sched& S, const Epi& E) {
;     ...
;             PG8_WAIT_V(8); PG8_WAIT_L(0); PG8_BAR; PG8_MMA(0, 0, At, B0); PG8_MMA(0, 1, At, B1); PG8_BAR; PG8_SCHED;
;             PG8_LDA(At, 1, 1); PG8_STAGE(PG8_SB(1, 0), b3, voffB); PG8_STAGE(PG8_SB(1, 1), b3 + hsB, voffB); PG8_STAGE(PG8_SA(1, 0), a3, voffA);
;             PG8_WAIT_V(8); PG8_WAIT_L(0); PG8_BAR; PG8_MMA(1, 0, At, B0); PG8_MMA(1, 1, At, B1); PG8_BAR; PG8_SCHED;
	s_setprio 3
	s_waitcnt lgkmcnt(0)
	v_mfma_f32_16x16x32_bf16 v[124:127], v[140:143], v[184:187], v[124:127]
	v_mfma_f32_16x16x32_bf16 v[124:127], v[156:159], v[188:191], v[124:127]
	v_mfma_f32_16x16x32_bf16 v[120:123], v[160:163], v[184:187], v[120:123]
	v_mfma_f32_16x16x32_bf16 v[120:123], v[164:167], v[188:191], v[120:123]
	v_mfma_f32_16x16x32_bf16 v[108:111], v[140:143], v[192:195], v[108:111]
	v_mfma_f32_16x16x32_bf16 v[108:111], v[156:159], v[196:199], v[108:111]
	v_mfma_f32_16x16x32_bf16 v[104:107], v[160:163], v[192:195], v[104:107]
	v_mfma_f32_16x16x32_bf16 v[104:107], v[164:167], v[196:199], v[104:107]
	v_mfma_f32_16x16x32_bf16 v[92:95], v[140:143], v[200:203], v[92:95]
	v_mfma_f32_16x16x32_bf16 v[92:95], v[156:159], v[204:207], v[92:95]
	v_mfma_f32_16x16x32_bf16 v[88:91], v[160:163], v[200:203], v[88:91]
	v_mfma_f32_16x16x32_bf16 v[88:91], v[164:167], v[204:207], v[88:91]
	v_mfma_f32_16x16x32_bf16 v[76:79], v[140:143], v[208:211], v[76:79]
	v_mfma_f32_16x16x32_bf16 v[76:79], v[156:159], v[212:215], v[76:79]
	v_mfma_f32_16x16x32_bf16 v[72:75], v[160:163], v[208:211], v[72:75]
	v_mfma_f32_16x16x32_bf16 v[72:75], v[164:167], v[212:215], v[72:75]
	s_setprio 0
	s_setprio 3
	v_mfma_f32_16x16x32_bf16 v[116:119], v[168:171], v[184:187], v[116:119]
	v_mfma_f32_16x16x32_bf16 v[116:119], v[172:175], v[188:191], v[116:119]
	v_mfma_f32_16x16x32_bf16 v[112:115], v[176:179], v[184:187], v[112:115]
	v_mfma_f32_16x16x32_bf16 v[112:115], v[180:183], v[188:191], v[112:115]
	v_mfma_f32_16x16x32_bf16 v[100:103], v[168:171], v[192:195], v[100:103]
	v_mfma_f32_16x16x32_bf16 v[100:103], v[172:175], v[196:199], v[100:103]
	v_mfma_f32_16x16x32_bf16 v[96:99], v[176:179], v[192:195], v[96:99]
	v_mfma_f32_16x16x32_bf16 v[96:99], v[180:183], v[196:199], v[96:99]
	v_mfma_f32_16x16x32_bf16 v[84:87], v[168:171], v[200:203], v[84:87]
	v_mfma_f32_16x16x32_bf16 v[84:87], v[172:175], v[204:207], v[84:87]
	v_mfma_f32_16x16x32_bf16 v[80:83], v[176:179], v[200:203], v[80:83]
	v_mfma_f32_16x16x32_bf16 v[80:83], v[180:183], v[204:207], v[80:83]
	v_mfma_f32_16x16x32_bf16 v[68:71], v[168:171], v[208:211], v[68:71]
	v_mfma_f32_16x16x32_bf16 v[68:71], v[172:175], v[212:215], v[68:71]
	v_mfma_f32_16x16x32_bf16 v[64:67], v[176:179], v[208:211], v[64:67]
	v_mfma_f32_16x16x32_bf16 v[64:67], v[180:183], v[212:215], v[64:67]
	s_setprio 0
	s_barrier
	s_add_i32 s20, s51, s25
	v_lshl_add_u64 v[144:145], v[144:145], 0, s[8:9]
	s_mov_b32 m0, s20
	ds_read_b128 v[184:187], v151 offset:49152
	ds_read_b128 v[188:191], v250 offset:49152
	ds_read_b128 v[192:195], v151 offset:51200
	ds_read_b128 v[196:199], v250 offset:51200
	ds_read_b128 v[200:203], v151 offset:53248
	ds_read_b128 v[204:207], v250 offset:53248
	ds_read_b128 v[208:211], v151 offset:55296
	ds_read_b128 v[212:215], v250 offset:55296
	global_load_lds_dwordx4 v[144:145], off
	s_add_i32 m0, s20, 0x2000
	s_add_u32 s16, s16, 0x404080
	v_lshl_add_u64 v[144:145], v[216:217], 0, s[8:9]
	s_addc_u32 s17, s17, 0
	s_add_i32 s20, s52, s25
	global_load_lds_dwordx4 v[144:145], off
	v_lshl_add_u64 v[144:145], s[16:17], 0, v[128:129]
	s_mov_b32 m0, s20
	s_nop 0
	global_load_lds_dwordx4 v[144:145], off
	v_lshl_add_u64 v[144:145], s[16:17], 0, v[130:131]
	s_add_i32 m0, s20, 0x2000
	s_nop 0
	global_load_lds_dwordx4 v[144:145], off
	s_waitcnt vmcnt(6)
	s_waitcnt lgkmcnt(0)
	s_barrier
	s_setprio 3
	s_waitcnt lgkmcnt(0)
	v_mfma_f32_16x16x32_bf16 v[60:63], v[140:143], v[184:187], v[60:63]
	v_mfma_f32_16x16x32_bf16 v[60:63], v[156:159], v[188:191], v[60:63]
	v_mfma_f32_16x16x32_bf16 v[56:59], v[160:163], v[184:187], v[56:59]
	v_mfma_f32_16x16x32_bf16 v[56:59], v[164:167], v[188:191], v[56:59]
	v_mfma_f32_16x16x32_bf16 v[44:47], v[140:143], v[192:195], v[44:47]
	v_mfma_f32_16x16x32_bf16 v[44:47], v[156:159], v[196:199], v[44:47]
	v_mfma_f32_16x16x32_bf16 v[40:43], v[160:163], v[192:195], v[40:43]
	v_mfma_f32_16x16x32_bf16 v[40:43], v[164:167], v[196:199], v[40:43]
	v_mfma_f32_16x16x32_bf16 v[28:31], v[140:143], v[200:203], v[28:31]
	v_mfma_f32_16x16x32_bf16 v[28:31], v[156:159], v[204:207], v[28:31]
	v_mfma_f32_16x16x32_bf16 v[24:27], v[160:163], v[200:203], v[24:27]
	v_mfma_f32_16x16x32_bf16 v[24:27], v[164:167], v[204:207], v[24:27]
	v_mfma_f32_16x16x32_bf16 v[12:15], v[140:143], v[208:211], v[12:15]
	v_mfma_f32_16x16x32_bf16 v[12:15], v[156:159], v[212:215], v[12:15]
	v_mfma_f32_16x16x32_bf16 v[8:11], v[160:163], v[208:211], v[8:11]
	v_mfma_f32_16x16x32_bf16 v[8:11], v[164:167], v[212:215], v[8:11]
	s_setprio 0
	s_setprio 3
	v_mfma_f32_16x16x32_bf16 v[52:55], v[168:171], v[184:187], v[52:55]
	v_mfma_f32_16x16x32_bf16 v[52:55], v[172:175], v[188:191], v[52:55]
	v_mfma_f32_16x16x32_bf16 v[48:51], v[176:179], v[184:187], v[48:51]
	v_mfma_f32_16x16x32_bf16 v[48:51], v[180:183], v[188:191], v[48:51]
	v_mfma_f32_16x16x32_bf16 v[36:39], v[168:171], v[192:195], v[36:39]
	v_mfma_f32_16x16x32_bf16 v[36:39], v[172:175], v[196:199], v[36:39]
	v_mfma_f32_16x16x32_bf16 v[32:35], v[176:179], v[192:195], v[32:35]
	v_mfma_f32_16x16x32_bf16 v[32:35], v[180:183], v[196:199], v[32:35]
	v_mfma_f32_16x16x32_bf16 v[20:23], v[168:171], v[200:203], v[20:23]
	v_mfma_f32_16x16x32_bf16 v[20:23], v[172:175], v[204:207], v[20:23]
	v_mfma_f32_16x16x32_bf16 v[16:19], v[176:179], v[200:203], v[16:19]
	v_mfma_f32_16x16x32_bf16 v[16:19], v[180:183], v[204:207], v[16:19]
	v_mfma_f32_16x16x32_bf16 v[4:7], v[168:171], v[208:211], v[4:7]
	v_mfma_f32_16x16x32_bf16 v[4:7], v[172:175], v[212:215], v[4:7]
	v_mfma_f32_16x16x32_bf16 v[0:3], v[176:179], v[208:211], v[0:3]
	v_mfma_f32_16x16x32_bf16 v[0:3], v[180:183], v[212:215], v[0:3]
	s_setprio 0
	s_barrier
	s_add_i32 s50, s50, 2
	s_add_u32 s14, s14, 0x100
	s_addc_u32 s15, s15, 0
	s_add_u32 s48, s48, 0x100
	s_addc_u32 s49, s49, 0
	s_cmpk_gt_u32 s50, 0xfd
	s_cbranch_scc0 .LBB0_350
	s_and_b64 vcc, exec, s[10:11]
	s_cbranch_vccz .LBB0_353
	s_barrier
